# MLA KV loop: two KV tiles per workgroup barrier (4 K buffers, 4 V^T slots in LDS), rest as diet6
# baseline (speedup 1.0000x reference)
; template <int DQK, int DV, int RH, bool NEGM> ...
;     ...
;     AT_GLOAD(0); AT_LSTORE(0, 0); __syncthreads();
;     int vs_prev = 2, vs_cur = 0, vs_next = 1;
;     if (!grpB) {
;         for (int t = 0; t < NT; ++t) {
;             const int kb = t & 1;
;             if (t + 1 < NT) AT_GLOAD(t + 1);
.LBB0_871:
	s_or_b64 exec, exec, s[44:45]
	v_mul_lo_u32 v5, v8, s57
	v_and_b32_e32 v241, 6, v132
	v_lshlrev_b32_e32 v241, 4, v241
	v_and_b32_e32 v242, 1, v132
	v_lshl_or_b32 v241, v242, 3, v241
	v_add3_u32 v166, 0, v5, v241
	v_add_u32_e32 v5, 0x6800, v166
	v_add_u32_e32 v243, 0x6800, v166
	v_add_u32_e32 v246, 0x8c00, v166
	v_add_u32_e32 v247, 0xb000, v166
	v_add_u32_e32 v248, 0xd400, v166
	s_waitcnt vmcnt(0)
	ds_write2_b64 v5, v[0:1], v[2:3] offset1:2
	s_waitcnt lgkmcnt(0)
	s_barrier
	s_and_saveexec_b64 s[44:45], s[6:7]
	s_cbranch_execz .LBB0_873
	v_add_u32_e32 v0, v136, v135
	v_mul_lo_u32 v1, v0, 12
	v_sub_u32_e32 v2, v133, v1
	v_add_u32_e32 v3, 64, v0
	v_mov_b64_e32 v[0:1], s[42:43]
	v_lshlrev_b32_e32 v2, 3, v2
	v_mad_i64_i32 v[0:1], s[62:63], v3, s51, v[0:1]
	v_ashrrev_i32_e32 v3, 31, v2
	v_lshl_add_u64 v[0:1], v[2:3], 1, v[0:1]
	global_load_dwordx4 v[104:107], v[0:1], off

; #define AT_QK_LD0(kb_) do { if constexpr (NEGM) { const LAS unsigned char* kbp_ = Kl + (kb_) * KBUF + r32 * KROWB + hi * 16; AT_KLD2(0); __builtin_amdgcn_sched_barrier(0); } } while (0)
; template <int DQK, int DV, int RH, bool NEGM> ...
;     ...
;     const int NT = nkv / 64;
;     AT_GLOAD(0); AT_LSTORE(0, 0); __syncthreads();
;     int vs_prev = 2, vs_cur = 0, vs_next = 1;
;     if (!grpB) {
;         for (int t = 0; t < NT; ++t) {
;             const int kb = t & 1;
;             if (t + 1 < NT) AT_GLOAD(t + 1);
;             f32x16 p[RH][2];
;             AT_QK_LD0(kb); AT_QK(kb); AT_VLOAD(vs_cur); AT_SOFTMAX(); AT_PV(vs_cur);
.LBB0_881:
	s_or_b64 exec, exec, s[42:43]
	v_pk_add_f32 v[48:49], v[48:49], v[54:55]
	v_pk_add_f32 v[64:65], v[128:129], v[64:65]
	v_pk_add_f32 v[48:49], v[58:59], v[48:49] op_sel_hi:[0,1]
	v_pk_add_f32 v[52:53], v[52:53], v[56:57]
	v_pk_add_f32 v[48:49], v[64:65], v[48:49]
	v_pk_add_f32 v[70:71], v[118:119], v[70:71]
	v_pk_add_f32 v[48:49], v[52:53], v[48:49]
	v_add_u32_e32 v54, v136, v135
	v_pk_add_f32 v[150:151], v[70:71], v[48:49]
	v_add_u32_e32 v48, 0x8c00, v166
	s_waitcnt vmcnt(0)
	ds_write2_b64 v48, v[74:75], v[76:77] offset1:2
	v_mul_lo_u32 v48, v54, 12
	v_sub_u32_e32 v52, v133, v48
	s_lshr_b32 s21, s61, 4
	v_lshlrev_b32_e32 v48, 3, v52
	v_lshlrev_b32_e32 v175, 4, v52
	v_mov_b64_e32 v[52:53], s[40:41]
	s_and_b32 s42, s21, 7
	v_mul_lo_u32 v174, v54, s56
	v_mad_i64_i32 v[54:55], s[40:41], v54, s51, v[52:53]
	v_pk_add_f32 v[50:51], v[50:51], v[62:63]
	v_ashrrev_i32_e32 v49, 31, v48
	v_mad_u64_u32 v[54:55], s[40:41], s42, v163, v[54:55]
	v_pk_add_f32 v[66:67], v[130:131], v[66:67]
	v_pk_add_f32 v[50:51], v[58:59], v[50:51] op_sel_hi:[0,1]
	v_lshl_add_u64 v[48:49], v[48:49], 1, v[54:55]
	v_pk_add_f32 v[56:57], v[116:117], v[68:69]
	v_pk_add_f32 v[50:51], v[66:67], v[50:51]
	v_mov_b32_e32 v154, v48
	v_mad_i64_i32 v[48:49], s[40:41], v59, s51, v[52:53]
	v_pk_add_f32 v[60:61], v[60:61], v[72:73]
	v_pk_add_f32 v[50:51], v[56:57], v[50:51]
	s_lshl_b32 s43, s42, 6
	v_mad_u64_u32 v[48:49], s[40:41], s42, v163, v[48:49]
	v_pk_add_f32 v[152:153], v[60:61], v[50:51]
	v_lshlrev_b32_e32 v50, 3, v112
	s_add_i32 s40, s47, s43
	v_ashrrev_i32_e32 v51, 31, v50
	s_ashr_i32 s41, s40, 31
	v_lshl_add_u64 v[48:49], v[50:51], 1, v[48:49]
	s_lshl_b64 s[40:41], s[40:41], 13
	v_and_b32_e32 v50, 7, v132
	v_mov_b32_e32 v156, v48
	v_lshl_add_u64 v[48:49], v[78:79], 0, s[40:41]
	v_lshlrev_b32_e32 v148, 4, v50
	v_lshl_add_u64 v[48:49], v[48:49], 0, v[148:149]
	v_mul_u32_u24_e32 v173, 0x90, v134
	s_mov_b32 s21, 1
	v_mov_b32_e32 v158, v48
	s_mov_b32 s42, 2
	s_mov_b32 s43, 1
	s_waitcnt lgkmcnt(0)
	s_barrier
	s_mov_b64 s[98:99], s[28:29]
	s_mov_b64 s[100:101], s[30:31]
	v_add_u32_e32 v244, v174, v175
	v_add_u32_e32 v245, v171, v172
	v_add_u32_e32 v251, 0xf800, v169
	global_load_dwordx4 v[104:107], v154, s[98:99]
	s_mov_b64 exec, s[8:9]
	global_load_dwordx4 v[108:111], v156, s[98:99]
	s_mov_b64 exec, -1
	global_load_dwordx4 v[112:115], v158, s[100:101]
	s_add_u32 s98, s98, 0x18000
	s_addc_u32 s99, s99, 0
	s_add_u32 s100, s100, 0x80
	s_addc_u32 s101, s101, 0
	v_add_u32_e32 v249, 0xf800, v244
	v_add_u32_e32 v250, 0xf800, v245
	ds_read_b128 v[48:51], v169 offset:13312
	ds_read_b128 v[52:55], v169 offset:13344
	ds_read_b128 v[116:119], v169 offset:19968
	ds_read_b128 v[120:123], v169 offset:20000
	s_waitcnt lgkmcnt(3)
	v_mfma_f32_32x32x16_bf16 v[64:79], v[48:51], v[100:103], v[32:47]
	ds_read_b128 v[124:127], v169 offset:13376
	ds_read_b128 v[128:131], v169 offset:13408
	ds_read_b128 v[132:135], v169 offset:20032
	ds_read_b128 v[136:139], v169 offset:20064
	s_waitcnt lgkmcnt(4)
	v_mfma_f32_32x32x16_bf16 v[64:79], v[52:55], v[96:99], v[64:79]
	v_mfma_f32_32x32x16_bf16 v[48:63], v[116:119], v[100:103], v[32:47]
	v_mfma_f32_32x32x16_bf16 v[48:63], v[120:123], v[96:99], v[48:63]
	s_waitcnt lgkmcnt(1)
	v_mfma_f32_32x32x16_bf16 v[64:79], v[124:127], v[92:95], v[64:79]
	v_mfma_f32_32x32x16_bf16 v[48:63], v[132:135], v[92:95], v[48:63]
	v_mfma_f32_32x32x16_bf16 v[64:79], v[128:131], v[88:91], v[64:79]
	ds_read_b128 v[116:119], v169 offset:13440
	ds_read_b128 v[120:123], v169 offset:13472
	ds_read_b128 v[128:131], v169 offset:20096
	ds_read_b128 v[176:179], v169 offset:20128
	s_waitcnt lgkmcnt(3)
	v_mfma_f32_32x32x16_bf16 v[48:63], v[136:139], v[88:91], v[48:63]
	v_mfma_f32_32x32x16_bf16 v[64:79], v[116:119], v[84:87], v[64:79]
	ds_read_b128 v[136:139], v170 offset:35840
	ds_read_b128 v[124:127], v170 offset:35872
	s_waitcnt lgkmcnt(3)
	v_mfma_f32_32x32x16_bf16 v[48:63], v[128:131], v[84:87], v[48:63]
	v_mfma_f32_32x32x16_bf16 v[64:79], v[120:123], v[80:83], v[64:79]
	ds_read_b128 v[132:135], v170 offset:35904
	ds_read_b128 v[120:123], v170 offset:35936
	ds_read_b128 v[144:147], v170 offset:40448
	ds_read_b128 v[140:143], v170 offset:40480
	ds_read_b128 v[128:131], v170 offset:40512
	ds_read_b128 v[116:119], v170 offset:40544
	s_waitcnt lgkmcnt(8)
	v_mfma_f32_32x32x16_bf16 v[48:63], v[176:179], v[80:83], v[48:63]
	s_add_i32 s43, s43, 1
	s_nop 10
	v_max_f32_e32 v148, v64, v48
	v_max_f32_e32 v160, v65, v49
	v_max_f32_e32 v161, v67, v51
	v_max3_f32 v176, v66, v50, v70
	v_max3_f32 v161, v161, v71, v55
	v_max3_f32 v148, v148, v68, v52
	v_max3_f32 v160, v160, v69, v53
	v_max3_f32 v176, v176, v54, v74
	v_max3_f32 v161, v161, v75, v59
	v_max3_f32 v148, v148, v72, v56
	v_max3_f32 v160, v160, v73, v57
	v_max3_f32 v176, v176, v58, v78
	v_max3_f32 v161, v161, v79, v63
	v_max3_f32 v148, v148, v76, v60
	v_max3_f32 v160, v160, v77, v61
	v_max3_f32 v161, v176, v62, v161
	v_max3_f32 v148, v148, v160, v161
	v_cmp_lt_f32_e32 vcc, s59, v148
	s_cbranch_vccz .Lmla_nr_b
; #define AT_QK_LD0(kb_) do { if constexpr (NEGM) { const LAS unsigned char* kbp_ = Kl + (kb_) * KBUF + r32 * KROWB + hi * 16; AT_KLD2(0); __builtin_amdgcn_sched_barrier(0); } } while (0)
; template <int DQK, int DV, int RH, bool NEGM> ...
;     ...
;     const int NT = nkv / 64;
;     AT_GLOAD(0); AT_LSTORE(0, 0); __syncthreads();
;     int vs_prev = 2, vs_cur = 0, vs_next = 1;
;     if (!grpB) {
;         for (int t = 0; t < NT; ++t) {
;             const int kb = t & 1;
;             if (t + 1 < NT) AT_GLOAD(t + 1);
;             f32x16 p[RH][2];
;             AT_QK_LD0(kb); AT_QK(kb); AT_VLOAD(vs_cur); AT_SOFTMAX(); AT_PV(vs_cur);
;             if (t + 1 < NT) AT_LSTORE(kb ^ 1, vs_next);
;             __syncthreads();
;             vs_prev = vs_cur; vs_cur = vs_next; vs_next = (vs_next == 2) ? 0 : vs_next + 1;
	v_mov_b32_e32 v160, v148
	s_nop 1
	v_permlane32_swap_b32_e32 v148, v160
	v_max_f32_e32 v148, v148, v160
	v_max_f32_e32 v32, v148, v148
	v_max_f32_e32 v148, 0, v32
	v_exp_f32_e64 v160, -v148
	v_add_f32_e32 v168, v168, v148
	v_xor_b32_e32 v32, 0x80000000, v168
	v_mov_b32_e32 v33, v32
	v_mov_b32_e32 v34, v32
	v_mov_b32_e32 v35, v32
	v_mov_b32_e32 v36, v32
	v_mov_b32_e32 v37, v32
	v_mov_b32_e32 v38, v32
	v_mov_b32_e32 v39, v32
	v_mov_b32_e32 v40, v32
	v_mov_b32_e32 v41, v32
	v_mov_b32_e32 v42, v32
	v_mov_b32_e32 v43, v32
	v_mov_b32_e32 v44, v32
	v_mov_b32_e32 v45, v32
	v_mov_b32_e32 v46, v32
	v_mov_b32_e32 v47, v32
	v_pk_add_f32 v[64:65], v[64:65], v[148:149] op_sel_hi:[1,0] neg_lo:[0,1] neg_hi:[0,1]
	v_pk_add_f32 v[48:49], v[48:49], v[148:149] op_sel_hi:[1,0] neg_lo:[0,1] neg_hi:[0,1]
	v_pk_add_f32 v[66:67], v[66:67], v[148:149] op_sel_hi:[1,0] neg_lo:[0,1] neg_hi:[0,1]
	v_pk_add_f32 v[50:51], v[50:51], v[148:149] op_sel_hi:[1,0] neg_lo:[0,1] neg_hi:[0,1]
	v_pk_add_f32 v[68:69], v[68:69], v[148:149] op_sel_hi:[1,0] neg_lo:[0,1] neg_hi:[0,1]
	v_pk_add_f32 v[52:53], v[52:53], v[148:149] op_sel_hi:[1,0] neg_lo:[0,1] neg_hi:[0,1]
	v_pk_add_f32 v[70:71], v[70:71], v[148:149] op_sel_hi:[1,0] neg_lo:[0,1] neg_hi:[0,1]
	v_pk_add_f32 v[54:55], v[54:55], v[148:149] op_sel_hi:[1,0] neg_lo:[0,1] neg_hi:[0,1]
	v_pk_add_f32 v[72:73], v[72:73], v[148:149] op_sel_hi:[1,0] neg_lo:[0,1] neg_hi:[0,1]
	v_pk_add_f32 v[56:57], v[56:57], v[148:149] op_sel_hi:[1,0] neg_lo:[0,1] neg_hi:[0,1]
	v_pk_add_f32 v[74:75], v[74:75], v[148:149] op_sel_hi:[1,0] neg_lo:[0,1] neg_hi:[0,1]
	v_pk_add_f32 v[58:59], v[58:59], v[148:149] op_sel_hi:[1,0] neg_lo:[0,1] neg_hi:[0,1]
	v_pk_add_f32 v[76:77], v[76:77], v[148:149] op_sel_hi:[1,0] neg_lo:[0,1] neg_hi:[0,1]
	v_pk_add_f32 v[60:61], v[60:61], v[148:149] op_sel_hi:[1,0] neg_lo:[0,1] neg_hi:[0,1]
	v_pk_add_f32 v[78:79], v[78:79], v[148:149] op_sel_hi:[1,0] neg_lo:[0,1] neg_hi:[0,1]
	v_pk_add_f32 v[62:63], v[62:63], v[148:149] op_sel_hi:[1,0] neg_lo:[0,1] neg_hi:[0,1]
	v_pk_mul_f32 v[30:31], v[30:31], v[160:161] op_sel_hi:[1,0]
	v_pk_mul_f32 v[28:29], v[28:29], v[160:161] op_sel_hi:[1,0]
	v_pk_mul_f32 v[26:27], v[26:27], v[160:161] op_sel_hi:[1,0]
	v_pk_mul_f32 v[24:25], v[24:25], v[160:161] op_sel_hi:[1,0]
	v_pk_mul_f32 v[22:23], v[22:23], v[160:161] op_sel_hi:[1,0]
	v_pk_mul_f32 v[20:21], v[20:21], v[160:161] op_sel_hi:[1,0]
	v_pk_mul_f32 v[18:19], v[18:19], v[160:161] op_sel_hi:[1,0]
	v_pk_mul_f32 v[16:17], v[16:17], v[160:161] op_sel_hi:[1,0]
	v_pk_mul_f32 v[14:15], v[14:15], v[160:161] op_sel_hi:[1,0]
	v_pk_mul_f32 v[12:13], v[12:13], v[160:161] op_sel_hi:[1,0]
	v_pk_mul_f32 v[10:11], v[10:11], v[160:161] op_sel_hi:[1,0]
	v_pk_mul_f32 v[8:9], v[8:9], v[160:161] op_sel_hi:[1,0]
	v_pk_mul_f32 v[6:7], v[6:7], v[160:161] op_sel_hi:[1,0]
	v_pk_mul_f32 v[4:5], v[4:5], v[160:161] op_sel_hi:[1,0]
	v_pk_mul_f32 v[2:3], v[2:3], v[160:161] op_sel_hi:[1,0]
	v_pk_mul_f32 v[0:1], v[0:1], v[160:161] op_sel_hi:[1,0]
	v_pk_mul_f32 v[152:153], v[152:153], v[160:161] op_sel_hi:[1,0]
	v_pk_mul_f32 v[150:151], v[150:151], v[160:161] op_sel_hi:[1,0]
.Lmla_nr_b:
	v_exp_f32_e32 v160, v64
	v_exp_f32_e32 v161, v65
	v_exp_f32_e32 v64, v66
	v_exp_f32_e32 v65, v67
	v_exp_f32_e32 v68, v68
	v_exp_f32_e32 v69, v69
	v_exp_f32_e32 v66, v70
	v_exp_f32_e32 v67, v71
	v_cvt_pk_bf16_f32 v176, v160, v161
	v_cvt_pk_bf16_f32 v177, v64, v65
	v_cvt_pk_bf16_f32 v178, v68, v69
	v_cvt_pk_bf16_f32 v179, v66, v67
	v_exp_f32_e32 v70, v74
	v_exp_f32_e32 v71, v75
	s_waitcnt lgkmcnt(0)
	v_mfma_f32_32x32x16_bf16 v[16:31], v[136:139], v[176:179], v[16:31]
	v_exp_f32_e32 v136, v72
	v_exp_f32_e32 v137, v73
	v_exp_f32_e32 v74, v76
	v_exp_f32_e32 v75, v77
	v_exp_f32_e32 v72, v78
	v_exp_f32_e32 v73, v79
	v_exp_f32_e32 v76, v48
	v_mfma_f32_32x32x16_bf16 v[0:15], v[144:147], v[176:179], v[0:15]
	v_cvt_pk_bf16_f32 v144, v136, v137
	v_cvt_pk_bf16_f32 v145, v70, v71
	v_cvt_pk_bf16_f32 v146, v74, v75
	v_cvt_pk_bf16_f32 v147, v72, v73
	v_exp_f32_e32 v77, v49
	v_exp_f32_e32 v48, v50
	v_exp_f32_e32 v49, v51
	v_mfma_f32_32x32x16_bf16 v[16:31], v[124:127], v[144:147], v[16:31]
	v_exp_f32_e32 v52, v52
	v_exp_f32_e32 v53, v53
	v_exp_f32_e32 v50, v54
	v_exp_f32_e32 v51, v55
	v_cvt_pk_bf16_f32 v124, v76, v77
	v_cvt_pk_bf16_f32 v125, v48, v49
	v_cvt_pk_bf16_f32 v126, v52, v53
	v_mfma_f32_32x32x16_bf16 v[0:15], v[140:143], v[144:147], v[0:15]
	v_cvt_pk_bf16_f32 v127, v50, v51
	v_exp_f32_e32 v78, v56
	v_exp_f32_e32 v79, v57
	v_exp_f32_e32 v54, v58
	v_exp_f32_e32 v55, v59
	v_exp_f32_e32 v58, v60
	v_exp_f32_e32 v59, v61
	v_mfma_f32_32x32x16_bf16 v[16:31], v[132:135], v[124:127], v[16:31]
	v_exp_f32_e32 v56, v62
	v_exp_f32_e32 v57, v63
	v_cvt_pk_bf16_f32 v60, v78, v79
	v_cvt_pk_bf16_f32 v61, v54, v55
	v_cvt_pk_bf16_f32 v62, v58, v59
	v_cvt_pk_bf16_f32 v63, v56, v57
	v_mfma_f32_32x32x16_bf16 v[0:15], v[128:131], v[124:127], v[0:15]
	v_mfma_f32_32x32x16_bf16 v[16:31], v[120:123], v[60:63], v[16:31]
	v_mfma_f32_32x32x16_bf16 v[0:15], v[116:119], v[60:63], v[0:15]
	s_waitcnt vmcnt(1)
	ds_write_b128 v249, v[104:107]
	s_mov_b64 exec, s[8:9]
	ds_write_b128 v250, v[108:111]
	s_mov_b64 exec, -1
	s_waitcnt vmcnt(0)
	ds_write2_b64 v247, v[112:113], v[114:115] offset1:2
	global_load_dwordx4 v[104:107], v154, s[98:99]
	s_mov_b64 exec, s[8:9]
	global_load_dwordx4 v[108:111], v156, s[98:99]
	s_mov_b64 exec, -1
	global_load_dwordx4 v[112:115], v158, s[100:101]
	s_add_u32 s98, s98, 0x18000
	s_addc_u32 s99, s99, 0
	s_add_u32 s100, s100, 0x80
	s_addc_u32 s101, s101, 0
	v_pk_add_f32 v[48:49], v[64:65], v[48:49]
	v_pk_add_f32 v[60:61], v[160:161], v[76:77]
	v_pk_add_f32 v[48:49], v[152:153], v[48:49]
	v_pk_add_f32 v[50:51], v[66:67], v[50:51]
	v_pk_add_f32 v[60:61], v[150:151], v[60:61]
	v_pk_add_f32 v[52:53], v[68:69], v[52:53]
	v_pk_add_f32 v[48:49], v[50:51], v[48:49]
	v_pk_add_f32 v[50:51], v[70:71], v[54:55]
	v_pk_add_f32 v[52:53], v[52:53], v[60:61]
	v_pk_add_f32 v[60:61], v[136:137], v[78:79]
	v_pk_add_f32 v[48:49], v[50:51], v[48:49]
	v_pk_add_f32 v[50:51], v[72:73], v[56:57]
	v_pk_add_f32 v[52:53], v[60:61], v[52:53]
	v_pk_add_f32 v[58:59], v[74:75], v[58:59]
	v_pk_add_f32 v[152:153], v[50:51], v[48:49]
	v_pk_add_f32 v[150:151], v[58:59], v[52:53]
	s_waitcnt vmcnt(1)
	ds_write_b128 v249, v[104:107] offset:13312
	s_mov_b64 exec, s[8:9]
	ds_write_b128 v250, v[108:111] offset:13312
	s_mov_b64 exec, -1
	s_waitcnt vmcnt(0)
	ds_write2_b64 v248, v[112:113], v[114:115] offset1:2
	global_load_dwordx4 v[104:107], v154, s[98:99]
	s_mov_b64 exec, s[8:9]
	global_load_dwordx4 v[108:111], v156, s[98:99]
	s_mov_b64 exec, -1
	global_load_dwordx4 v[112:115], v158, s[100:101]
	s_add_u32 s98, s98, 0x18000
	s_addc_u32 s99, s99, 0
	s_add_u32 s100, s100, 0x80
	s_addc_u32 s101, s101, 0
	s_waitcnt lgkmcnt(0)
	s_barrier
; #define AT_QK_LD0(kb_) do { if constexpr (NEGM) { const LAS unsigned char* kbp_ = Kl + (kb_) * KBUF + r32 * KROWB + hi * 16; AT_KLD2(0); __builtin_amdgcn_sched_barrier(0); } } while (0)
; template <int DQK, int DV, int RH, bool NEGM> ...
;     ...
;         for (int t = 0; t < NT; ++t) {
;             const int kb = t & 1;
;             if (t + 1 < NT) AT_GLOAD(t + 1);
;             f32x16 p[RH][2];
;             AT_QK_LD0(kb); AT_QK(kb); AT_VLOAD(vs_cur); AT_SOFTMAX(); AT_PV(vs_cur);
.Lmla_loop:
	ds_read_b128 v[48:51], v251
	ds_read_b128 v[52:55], v251 offset:32
	ds_read_b128 v[116:119], v251 offset:6656
	ds_read_b128 v[120:123], v251 offset:6688
	s_waitcnt lgkmcnt(3)
	v_mfma_f32_32x32x16_bf16 v[64:79], v[48:51], v[100:103], v[32:47]
	ds_read_b128 v[124:127], v251 offset:64
	ds_read_b128 v[128:131], v251 offset:96
	ds_read_b128 v[132:135], v251 offset:6720
	ds_read_b128 v[136:139], v251 offset:6752
	s_waitcnt lgkmcnt(4)
	v_mfma_f32_32x32x16_bf16 v[64:79], v[52:55], v[96:99], v[64:79]
	v_mfma_f32_32x32x16_bf16 v[48:63], v[116:119], v[100:103], v[32:47]
	v_mfma_f32_32x32x16_bf16 v[48:63], v[120:123], v[96:99], v[48:63]
	s_waitcnt lgkmcnt(1)
	v_mfma_f32_32x32x16_bf16 v[64:79], v[124:127], v[92:95], v[64:79]
	v_mfma_f32_32x32x16_bf16 v[48:63], v[132:135], v[92:95], v[48:63]
	v_mfma_f32_32x32x16_bf16 v[64:79], v[128:131], v[88:91], v[64:79]
	ds_read_b128 v[116:119], v251 offset:128
	ds_read_b128 v[120:123], v251 offset:160
	ds_read_b128 v[128:131], v251 offset:6784
	ds_read_b128 v[176:179], v251 offset:6816
	s_waitcnt lgkmcnt(3)
	v_mfma_f32_32x32x16_bf16 v[48:63], v[136:139], v[88:91], v[48:63]
	v_mfma_f32_32x32x16_bf16 v[64:79], v[116:119], v[84:87], v[64:79]
	ds_read_b128 v[136:139], v170 offset:45056
	ds_read_b128 v[124:127], v170 offset:45088
	s_waitcnt lgkmcnt(3)
	v_mfma_f32_32x32x16_bf16 v[48:63], v[128:131], v[84:87], v[48:63]
	v_mfma_f32_32x32x16_bf16 v[64:79], v[120:123], v[80:83], v[64:79]
	ds_read_b128 v[132:135], v170 offset:45120
	ds_read_b128 v[120:123], v170 offset:45152
	ds_read_b128 v[144:147], v170 offset:49664
	ds_read_b128 v[140:143], v170 offset:49696
	ds_read_b128 v[128:131], v170 offset:49728
	ds_read_b128 v[116:119], v170 offset:49760
	s_waitcnt lgkmcnt(8)
	v_mfma_f32_32x32x16_bf16 v[48:63], v[176:179], v[80:83], v[48:63]
	s_add_i32 s43, s43, 1
	s_nop 10
	v_max_f32_e32 v148, v64, v48
	v_max_f32_e32 v160, v65, v49
	v_max_f32_e32 v161, v67, v51
	v_max3_f32 v176, v66, v50, v70
	v_max3_f32 v161, v161, v71, v55
	v_max3_f32 v148, v148, v68, v52
	v_max3_f32 v160, v160, v69, v53
	v_max3_f32 v176, v176, v54, v74
	v_max3_f32 v161, v161, v75, v59
	v_max3_f32 v148, v148, v72, v56
	v_max3_f32 v160, v160, v73, v57
	v_max3_f32 v176, v176, v58, v78
	v_max3_f32 v161, v161, v79, v63
	v_max3_f32 v148, v148, v76, v60
	v_max3_f32 v160, v160, v77, v61
	v_max3_f32 v161, v176, v62, v161
	v_max3_f32 v148, v148, v160, v161
	v_cmp_lt_f32_e32 vcc, s59, v148
	s_cbranch_vccz .Lmla_nr_2
	v_mov_b32_e32 v160, v148
	s_nop 1
	v_permlane32_swap_b32_e32 v148, v160
	v_max_f32_e32 v148, v148, v160
	v_max_f32_e32 v32, v148, v148
	v_max_f32_e32 v148, 0, v32
	v_exp_f32_e64 v160, -v148
	v_add_f32_e32 v168, v168, v148
	v_xor_b32_e32 v32, 0x80000000, v168
	v_mov_b32_e32 v33, v32
	v_mov_b32_e32 v34, v32
	v_mov_b32_e32 v35, v32
	v_mov_b32_e32 v36, v32
	v_mov_b32_e32 v37, v32
	v_mov_b32_e32 v38, v32
	v_mov_b32_e32 v39, v32
	v_mov_b32_e32 v40, v32
	v_mov_b32_e32 v41, v32
	v_mov_b32_e32 v42, v32
	v_mov_b32_e32 v43, v32
	v_mov_b32_e32 v44, v32
	v_mov_b32_e32 v45, v32
	v_mov_b32_e32 v46, v32
	v_mov_b32_e32 v47, v32
	v_pk_add_f32 v[64:65], v[64:65], v[148:149] op_sel_hi:[1,0] neg_lo:[0,1] neg_hi:[0,1]
	v_pk_add_f32 v[48:49], v[48:49], v[148:149] op_sel_hi:[1,0] neg_lo:[0,1] neg_hi:[0,1]
	v_pk_add_f32 v[66:67], v[66:67], v[148:149] op_sel_hi:[1,0] neg_lo:[0,1] neg_hi:[0,1]
	v_pk_add_f32 v[50:51], v[50:51], v[148:149] op_sel_hi:[1,0] neg_lo:[0,1] neg_hi:[0,1]
	v_pk_add_f32 v[68:69], v[68:69], v[148:149] op_sel_hi:[1,0] neg_lo:[0,1] neg_hi:[0,1]
	v_pk_add_f32 v[52:53], v[52:53], v[148:149] op_sel_hi:[1,0] neg_lo:[0,1] neg_hi:[0,1]
	v_pk_add_f32 v[70:71], v[70:71], v[148:149] op_sel_hi:[1,0] neg_lo:[0,1] neg_hi:[0,1]
	v_pk_add_f32 v[54:55], v[54:55], v[148:149] op_sel_hi:[1,0] neg_lo:[0,1] neg_hi:[0,1]
	v_pk_add_f32 v[72:73], v[72:73], v[148:149] op_sel_hi:[1,0] neg_lo:[0,1] neg_hi:[0,1]
	v_pk_add_f32 v[56:57], v[56:57], v[148:149] op_sel_hi:[1,0] neg_lo:[0,1] neg_hi:[0,1]
	v_pk_add_f32 v[74:75], v[74:75], v[148:149] op_sel_hi:[1,0] neg_lo:[0,1] neg_hi:[0,1]
	v_pk_add_f32 v[58:59], v[58:59], v[148:149] op_sel_hi:[1,0] neg_lo:[0,1] neg_hi:[0,1]
	v_pk_add_f32 v[76:77], v[76:77], v[148:149] op_sel_hi:[1,0] neg_lo:[0,1] neg_hi:[0,1]
	v_pk_add_f32 v[60:61], v[60:61], v[148:149] op_sel_hi:[1,0] neg_lo:[0,1] neg_hi:[0,1]
	v_pk_add_f32 v[78:79], v[78:79], v[148:149] op_sel_hi:[1,0] neg_lo:[0,1] neg_hi:[0,1]
	v_pk_add_f32 v[62:63], v[62:63], v[148:149] op_sel_hi:[1,0] neg_lo:[0,1] neg_hi:[0,1]
	v_pk_mul_f32 v[30:31], v[30:31], v[160:161] op_sel_hi:[1,0]
	v_pk_mul_f32 v[28:29], v[28:29], v[160:161] op_sel_hi:[1,0]
	v_pk_mul_f32 v[26:27], v[26:27], v[160:161] op_sel_hi:[1,0]
	v_pk_mul_f32 v[24:25], v[24:25], v[160:161] op_sel_hi:[1,0]
	v_pk_mul_f32 v[22:23], v[22:23], v[160:161] op_sel_hi:[1,0]
	v_pk_mul_f32 v[20:21], v[20:21], v[160:161] op_sel_hi:[1,0]
	v_pk_mul_f32 v[18:19], v[18:19], v[160:161] op_sel_hi:[1,0]
	v_pk_mul_f32 v[16:17], v[16:17], v[160:161] op_sel_hi:[1,0]
	v_pk_mul_f32 v[14:15], v[14:15], v[160:161] op_sel_hi:[1,0]
	v_pk_mul_f32 v[12:13], v[12:13], v[160:161] op_sel_hi:[1,0]
	v_pk_mul_f32 v[10:11], v[10:11], v[160:161] op_sel_hi:[1,0]
	v_pk_mul_f32 v[8:9], v[8:9], v[160:161] op_sel_hi:[1,0]
	v_pk_mul_f32 v[6:7], v[6:7], v[160:161] op_sel_hi:[1,0]
	v_pk_mul_f32 v[4:5], v[4:5], v[160:161] op_sel_hi:[1,0]
	v_pk_mul_f32 v[2:3], v[2:3], v[160:161] op_sel_hi:[1,0]
	v_pk_mul_f32 v[0:1], v[0:1], v[160:161] op_sel_hi:[1,0]
	v_pk_mul_f32 v[152:153], v[152:153], v[160:161] op_sel_hi:[1,0]
	v_pk_mul_f32 v[150:151], v[150:151], v[160:161] op_sel_hi:[1,0]
; #define AT_QK_LD0(kb_) do { if constexpr (NEGM) { const LAS unsigned char* kbp_ = Kl + (kb_) * KBUF + r32 * KROWB + hi * 16; AT_KLD2(0); __builtin_amdgcn_sched_barrier(0); } } while (0)
; template <int DQK, int DV, int RH, bool NEGM> ...
;     ...
;     const int NT = nkv / 64;
;     AT_GLOAD(0); AT_LSTORE(0, 0); __syncthreads();
;     int vs_prev = 2, vs_cur = 0, vs_next = 1;
;     if (!grpB) {
;         for (int t = 0; t < NT; ++t) {
;             const int kb = t & 1;
;             if (t + 1 < NT) AT_GLOAD(t + 1);
;             f32x16 p[RH][2];
;             AT_QK_LD0(kb); AT_QK(kb); AT_VLOAD(vs_cur); AT_SOFTMAX(); AT_PV(vs_cur);
;             if (t + 1 < NT) AT_LSTORE(kb ^ 1, vs_next);
.Lmla_nr_2:
	v_exp_f32_e32 v160, v64
	v_exp_f32_e32 v161, v65
	v_exp_f32_e32 v64, v66
	v_exp_f32_e32 v65, v67
	v_exp_f32_e32 v68, v68
	v_exp_f32_e32 v69, v69
	v_exp_f32_e32 v66, v70
	v_exp_f32_e32 v67, v71
	v_cvt_pk_bf16_f32 v176, v160, v161
	v_cvt_pk_bf16_f32 v177, v64, v65
	v_cvt_pk_bf16_f32 v178, v68, v69
	v_cvt_pk_bf16_f32 v179, v66, v67
	v_exp_f32_e32 v70, v74
	v_exp_f32_e32 v71, v75
	s_waitcnt lgkmcnt(0)
	v_mfma_f32_32x32x16_bf16 v[16:31], v[136:139], v[176:179], v[16:31]
	v_exp_f32_e32 v136, v72
	v_exp_f32_e32 v137, v73
	v_exp_f32_e32 v74, v76
	v_exp_f32_e32 v75, v77
	v_exp_f32_e32 v72, v78
	v_exp_f32_e32 v73, v79
	v_exp_f32_e32 v76, v48
	v_mfma_f32_32x32x16_bf16 v[0:15], v[144:147], v[176:179], v[0:15]
	v_cvt_pk_bf16_f32 v144, v136, v137
	v_cvt_pk_bf16_f32 v145, v70, v71
	v_cvt_pk_bf16_f32 v146, v74, v75
	v_cvt_pk_bf16_f32 v147, v72, v73
	v_exp_f32_e32 v77, v49
	v_exp_f32_e32 v48, v50
	v_exp_f32_e32 v49, v51
	v_mfma_f32_32x32x16_bf16 v[16:31], v[124:127], v[144:147], v[16:31]
	v_exp_f32_e32 v52, v52
	v_exp_f32_e32 v53, v53
	v_exp_f32_e32 v50, v54
	v_exp_f32_e32 v51, v55
	v_cvt_pk_bf16_f32 v124, v76, v77
	v_cvt_pk_bf16_f32 v125, v48, v49
	v_cvt_pk_bf16_f32 v126, v52, v53
	v_mfma_f32_32x32x16_bf16 v[0:15], v[140:143], v[144:147], v[0:15]
	v_cvt_pk_bf16_f32 v127, v50, v51
	v_exp_f32_e32 v78, v56
	v_exp_f32_e32 v79, v57
	v_exp_f32_e32 v54, v58
	v_exp_f32_e32 v55, v59
	v_exp_f32_e32 v58, v60
	v_exp_f32_e32 v59, v61
	v_mfma_f32_32x32x16_bf16 v[16:31], v[132:135], v[124:127], v[16:31]
	v_exp_f32_e32 v56, v62
	v_exp_f32_e32 v57, v63
	v_cvt_pk_bf16_f32 v60, v78, v79
	v_cvt_pk_bf16_f32 v61, v54, v55
	v_cvt_pk_bf16_f32 v62, v58, v59
	v_cvt_pk_bf16_f32 v63, v56, v57
	v_mfma_f32_32x32x16_bf16 v[0:15], v[128:131], v[124:127], v[0:15]
	v_mfma_f32_32x32x16_bf16 v[16:31], v[120:123], v[60:63], v[16:31]
	v_mfma_f32_32x32x16_bf16 v[0:15], v[116:119], v[60:63], v[0:15]
	s_waitcnt vmcnt(1)
	ds_write_b128 v244, v[104:107]
	s_mov_b64 exec, s[8:9]
	ds_write_b128 v245, v[108:111]
	s_mov_b64 exec, -1
	s_waitcnt vmcnt(0)
	ds_write2_b64 v243, v[112:113], v[114:115] offset1:2
	global_load_dwordx4 v[104:107], v154, s[98:99]
	s_mov_b64 exec, s[8:9]
	global_load_dwordx4 v[108:111], v156, s[98:99]
	s_mov_b64 exec, -1
	global_load_dwordx4 v[112:115], v158, s[100:101]
	s_add_u32 s98, s98, 0x18000
	s_addc_u32 s99, s99, 0
	s_add_u32 s100, s100, 0x80
	s_addc_u32 s101, s101, 0
	v_pk_add_f32 v[48:49], v[64:65], v[48:49]
	v_pk_add_f32 v[60:61], v[160:161], v[76:77]
	v_pk_add_f32 v[48:49], v[152:153], v[48:49]
	v_pk_add_f32 v[50:51], v[66:67], v[50:51]
	v_pk_add_f32 v[60:61], v[150:151], v[60:61]
	v_pk_add_f32 v[52:53], v[68:69], v[52:53]
	v_pk_add_f32 v[48:49], v[50:51], v[48:49]
	v_pk_add_f32 v[50:51], v[70:71], v[54:55]
	v_pk_add_f32 v[52:53], v[52:53], v[60:61]
	v_pk_add_f32 v[60:61], v[136:137], v[78:79]
	v_pk_add_f32 v[48:49], v[50:51], v[48:49]
	v_pk_add_f32 v[50:51], v[72:73], v[56:57]
	v_pk_add_f32 v[52:53], v[60:61], v[52:53]
	v_pk_add_f32 v[58:59], v[74:75], v[58:59]
	v_pk_add_f32 v[152:153], v[50:51], v[48:49]
	v_pk_add_f32 v[150:151], v[58:59], v[52:53]
	ds_read_b128 v[48:51], v251 offset:13312
	ds_read_b128 v[52:55], v251 offset:13344
	ds_read_b128 v[116:119], v251 offset:19968
	ds_read_b128 v[120:123], v251 offset:20000
	s_waitcnt lgkmcnt(3)
	v_mfma_f32_32x32x16_bf16 v[64:79], v[48:51], v[100:103], v[32:47]
	ds_read_b128 v[124:127], v251 offset:13376
	ds_read_b128 v[128:131], v251 offset:13408
	ds_read_b128 v[132:135], v251 offset:20032
	ds_read_b128 v[136:139], v251 offset:20064
	s_waitcnt lgkmcnt(4)
	v_mfma_f32_32x32x16_bf16 v[64:79], v[52:55], v[96:99], v[64:79]
	v_mfma_f32_32x32x16_bf16 v[48:63], v[116:119], v[100:103], v[32:47]
	v_mfma_f32_32x32x16_bf16 v[48:63], v[120:123], v[96:99], v[48:63]
	s_waitcnt lgkmcnt(1)
	v_mfma_f32_32x32x16_bf16 v[64:79], v[124:127], v[92:95], v[64:79]
	v_mfma_f32_32x32x16_bf16 v[48:63], v[132:135], v[92:95], v[48:63]
	v_mfma_f32_32x32x16_bf16 v[64:79], v[128:131], v[88:91], v[64:79]
	ds_read_b128 v[116:119], v251 offset:13440
	ds_read_b128 v[120:123], v251 offset:13472
	ds_read_b128 v[128:131], v251 offset:20096
	ds_read_b128 v[176:179], v251 offset:20128
	s_waitcnt lgkmcnt(3)
	v_mfma_f32_32x32x16_bf16 v[48:63], v[136:139], v[88:91], v[48:63]
	v_mfma_f32_32x32x16_bf16 v[64:79], v[116:119], v[84:87], v[64:79]
	ds_read_b128 v[136:139], v170 offset:54272
	ds_read_b128 v[124:127], v170 offset:54304
	s_waitcnt lgkmcnt(3)
	v_mfma_f32_32x32x16_bf16 v[48:63], v[128:131], v[84:87], v[48:63]
	v_mfma_f32_32x32x16_bf16 v[64:79], v[120:123], v[80:83], v[64:79]
	ds_read_b128 v[132:135], v170 offset:54336
	ds_read_b128 v[120:123], v170 offset:54368
	ds_read_b128 v[144:147], v170 offset:58880
	ds_read_b128 v[140:143], v170 offset:58912
	ds_read_b128 v[128:131], v170 offset:58944
	ds_read_b128 v[116:119], v170 offset:58976
	s_waitcnt lgkmcnt(8)
	v_mfma_f32_32x32x16_bf16 v[48:63], v[176:179], v[80:83], v[48:63]
	s_add_i32 s43, s43, 1
	s_nop 10
	v_max_f32_e32 v148, v64, v48
	v_max_f32_e32 v160, v65, v49
	v_max_f32_e32 v161, v67, v51
	v_max3_f32 v176, v66, v50, v70
	v_max3_f32 v161, v161, v71, v55
	v_max3_f32 v148, v148, v68, v52
	v_max3_f32 v160, v160, v69, v53
	v_max3_f32 v176, v176, v54, v74
	v_max3_f32 v161, v161, v75, v59
	v_max3_f32 v148, v148, v72, v56
	v_max3_f32 v160, v160, v73, v57
	v_max3_f32 v176, v176, v58, v78
	v_max3_f32 v161, v161, v79, v63
	v_max3_f32 v148, v148, v76, v60
	v_max3_f32 v160, v160, v77, v61
	v_max3_f32 v161, v176, v62, v161
	v_max3_f32 v148, v148, v160, v161
	v_cmp_lt_f32_e32 vcc, s59, v148
	s_cbranch_vccz .Lmla_nr_3
; #define AT_QK_LD0(kb_) do { if constexpr (NEGM) { const LAS unsigned char* kbp_ = Kl + (kb_) * KBUF + r32 * KROWB + hi * 16; AT_KLD2(0); __builtin_amdgcn_sched_barrier(0); } } while (0)
; template <int DQK, int DV, int RH, bool NEGM> ...
;     ...
;     const int NT = nkv / 64;
;     AT_GLOAD(0); AT_LSTORE(0, 0); __syncthreads();
;     int vs_prev = 2, vs_cur = 0, vs_next = 1;
;     if (!grpB) {
;         for (int t = 0; t < NT; ++t) {
;             const int kb = t & 1;
;             if (t + 1 < NT) AT_GLOAD(t + 1);
;             f32x16 p[RH][2];
;             AT_QK_LD0(kb); AT_QK(kb); AT_VLOAD(vs_cur); AT_SOFTMAX(); AT_PV(vs_cur);
;             if (t + 1 < NT) AT_LSTORE(kb ^ 1, vs_next);
;             __syncthreads();
	v_mov_b32_e32 v160, v148
	s_nop 1
	v_permlane32_swap_b32_e32 v148, v160
	v_max_f32_e32 v148, v148, v160
	v_max_f32_e32 v32, v148, v148
	v_max_f32_e32 v148, 0, v32
	v_exp_f32_e64 v160, -v148
	v_add_f32_e32 v168, v168, v148
	v_xor_b32_e32 v32, 0x80000000, v168
	v_mov_b32_e32 v33, v32
	v_mov_b32_e32 v34, v32
	v_mov_b32_e32 v35, v32
	v_mov_b32_e32 v36, v32
	v_mov_b32_e32 v37, v32
	v_mov_b32_e32 v38, v32
	v_mov_b32_e32 v39, v32
	v_mov_b32_e32 v40, v32
	v_mov_b32_e32 v41, v32
	v_mov_b32_e32 v42, v32
	v_mov_b32_e32 v43, v32
	v_mov_b32_e32 v44, v32
	v_mov_b32_e32 v45, v32
	v_mov_b32_e32 v46, v32
	v_mov_b32_e32 v47, v32
	v_pk_add_f32 v[64:65], v[64:65], v[148:149] op_sel_hi:[1,0] neg_lo:[0,1] neg_hi:[0,1]
	v_pk_add_f32 v[48:49], v[48:49], v[148:149] op_sel_hi:[1,0] neg_lo:[0,1] neg_hi:[0,1]
	v_pk_add_f32 v[66:67], v[66:67], v[148:149] op_sel_hi:[1,0] neg_lo:[0,1] neg_hi:[0,1]
	v_pk_add_f32 v[50:51], v[50:51], v[148:149] op_sel_hi:[1,0] neg_lo:[0,1] neg_hi:[0,1]
	v_pk_add_f32 v[68:69], v[68:69], v[148:149] op_sel_hi:[1,0] neg_lo:[0,1] neg_hi:[0,1]
	v_pk_add_f32 v[52:53], v[52:53], v[148:149] op_sel_hi:[1,0] neg_lo:[0,1] neg_hi:[0,1]
	v_pk_add_f32 v[70:71], v[70:71], v[148:149] op_sel_hi:[1,0] neg_lo:[0,1] neg_hi:[0,1]
	v_pk_add_f32 v[54:55], v[54:55], v[148:149] op_sel_hi:[1,0] neg_lo:[0,1] neg_hi:[0,1]
	v_pk_add_f32 v[72:73], v[72:73], v[148:149] op_sel_hi:[1,0] neg_lo:[0,1] neg_hi:[0,1]
	v_pk_add_f32 v[56:57], v[56:57], v[148:149] op_sel_hi:[1,0] neg_lo:[0,1] neg_hi:[0,1]
	v_pk_add_f32 v[74:75], v[74:75], v[148:149] op_sel_hi:[1,0] neg_lo:[0,1] neg_hi:[0,1]
	v_pk_add_f32 v[58:59], v[58:59], v[148:149] op_sel_hi:[1,0] neg_lo:[0,1] neg_hi:[0,1]
	v_pk_add_f32 v[76:77], v[76:77], v[148:149] op_sel_hi:[1,0] neg_lo:[0,1] neg_hi:[0,1]
	v_pk_add_f32 v[60:61], v[60:61], v[148:149] op_sel_hi:[1,0] neg_lo:[0,1] neg_hi:[0,1]
	v_pk_add_f32 v[78:79], v[78:79], v[148:149] op_sel_hi:[1,0] neg_lo:[0,1] neg_hi:[0,1]
	v_pk_add_f32 v[62:63], v[62:63], v[148:149] op_sel_hi:[1,0] neg_lo:[0,1] neg_hi:[0,1]
	v_pk_mul_f32 v[30:31], v[30:31], v[160:161] op_sel_hi:[1,0]
	v_pk_mul_f32 v[28:29], v[28:29], v[160:161] op_sel_hi:[1,0]
	v_pk_mul_f32 v[26:27], v[26:27], v[160:161] op_sel_hi:[1,0]
	v_pk_mul_f32 v[24:25], v[24:25], v[160:161] op_sel_hi:[1,0]
	v_pk_mul_f32 v[22:23], v[22:23], v[160:161] op_sel_hi:[1,0]
	v_pk_mul_f32 v[20:21], v[20:21], v[160:161] op_sel_hi:[1,0]
	v_pk_mul_f32 v[18:19], v[18:19], v[160:161] op_sel_hi:[1,0]
	v_pk_mul_f32 v[16:17], v[16:17], v[160:161] op_sel_hi:[1,0]
	v_pk_mul_f32 v[14:15], v[14:15], v[160:161] op_sel_hi:[1,0]
	v_pk_mul_f32 v[12:13], v[12:13], v[160:161] op_sel_hi:[1,0]
	v_pk_mul_f32 v[10:11], v[10:11], v[160:161] op_sel_hi:[1,0]
	v_pk_mul_f32 v[8:9], v[8:9], v[160:161] op_sel_hi:[1,0]
	v_pk_mul_f32 v[6:7], v[6:7], v[160:161] op_sel_hi:[1,0]
	v_pk_mul_f32 v[4:5], v[4:5], v[160:161] op_sel_hi:[1,0]
	v_pk_mul_f32 v[2:3], v[2:3], v[160:161] op_sel_hi:[1,0]
	v_pk_mul_f32 v[0:1], v[0:1], v[160:161] op_sel_hi:[1,0]
	v_pk_mul_f32 v[152:153], v[152:153], v[160:161] op_sel_hi:[1,0]
	v_pk_mul_f32 v[150:151], v[150:151], v[160:161] op_sel_hi:[1,0]
.Lmla_nr_3:
	v_exp_f32_e32 v160, v64
	v_exp_f32_e32 v161, v65
	v_exp_f32_e32 v64, v66
	v_exp_f32_e32 v65, v67
	v_exp_f32_e32 v68, v68
	v_exp_f32_e32 v69, v69
	v_exp_f32_e32 v66, v70
	v_exp_f32_e32 v67, v71
	v_cvt_pk_bf16_f32 v176, v160, v161
	v_cvt_pk_bf16_f32 v177, v64, v65
	v_cvt_pk_bf16_f32 v178, v68, v69
	v_cvt_pk_bf16_f32 v179, v66, v67
	v_exp_f32_e32 v70, v74
	v_exp_f32_e32 v71, v75
	s_waitcnt lgkmcnt(0)
	v_mfma_f32_32x32x16_bf16 v[16:31], v[136:139], v[176:179], v[16:31]
	v_exp_f32_e32 v136, v72
	v_exp_f32_e32 v137, v73
	v_exp_f32_e32 v74, v76
	v_exp_f32_e32 v75, v77
	v_exp_f32_e32 v72, v78
	v_exp_f32_e32 v73, v79
	v_exp_f32_e32 v76, v48
	v_mfma_f32_32x32x16_bf16 v[0:15], v[144:147], v[176:179], v[0:15]
	v_cvt_pk_bf16_f32 v144, v136, v137
	v_cvt_pk_bf16_f32 v145, v70, v71
	v_cvt_pk_bf16_f32 v146, v74, v75
	v_cvt_pk_bf16_f32 v147, v72, v73
	v_exp_f32_e32 v77, v49
	v_exp_f32_e32 v48, v50
	v_exp_f32_e32 v49, v51
	v_mfma_f32_32x32x16_bf16 v[16:31], v[124:127], v[144:147], v[16:31]
	v_exp_f32_e32 v52, v52
	v_exp_f32_e32 v53, v53
	v_exp_f32_e32 v50, v54
	v_exp_f32_e32 v51, v55
	v_cvt_pk_bf16_f32 v124, v76, v77
	v_cvt_pk_bf16_f32 v125, v48, v49
	v_cvt_pk_bf16_f32 v126, v52, v53
	v_mfma_f32_32x32x16_bf16 v[0:15], v[140:143], v[144:147], v[0:15]
	v_cvt_pk_bf16_f32 v127, v50, v51
	v_exp_f32_e32 v78, v56
	v_exp_f32_e32 v79, v57
	v_exp_f32_e32 v54, v58
	v_exp_f32_e32 v55, v59
	v_exp_f32_e32 v58, v60
	v_exp_f32_e32 v59, v61
	v_mfma_f32_32x32x16_bf16 v[16:31], v[132:135], v[124:127], v[16:31]
	v_exp_f32_e32 v56, v62
	v_exp_f32_e32 v57, v63
	v_cvt_pk_bf16_f32 v60, v78, v79
	v_cvt_pk_bf16_f32 v61, v54, v55
	v_cvt_pk_bf16_f32 v62, v58, v59
	v_cvt_pk_bf16_f32 v63, v56, v57
	v_mfma_f32_32x32x16_bf16 v[0:15], v[128:131], v[124:127], v[0:15]
	v_mfma_f32_32x32x16_bf16 v[16:31], v[120:123], v[60:63], v[16:31]
	v_mfma_f32_32x32x16_bf16 v[0:15], v[116:119], v[60:63], v[0:15]
	s_waitcnt vmcnt(1)
	ds_write_b128 v244, v[104:107] offset:13312
	s_mov_b64 exec, s[8:9]
	ds_write_b128 v245, v[108:111] offset:13312
	s_mov_b64 exec, -1
	s_waitcnt vmcnt(0)
	ds_write2_b64 v246, v[112:113], v[114:115] offset1:2
	global_load_dwordx4 v[104:107], v154, s[98:99]
	s_mov_b64 exec, s[8:9]
	global_load_dwordx4 v[108:111], v156, s[98:99]
	s_mov_b64 exec, -1
	global_load_dwordx4 v[112:115], v158, s[100:101]
	s_add_u32 s98, s98, 0x18000
	s_addc_u32 s99, s99, 0
	s_add_u32 s100, s100, 0x80
	s_addc_u32 s101, s101, 0
	v_pk_add_f32 v[48:49], v[64:65], v[48:49]
	v_pk_add_f32 v[60:61], v[160:161], v[76:77]
	v_pk_add_f32 v[48:49], v[152:153], v[48:49]
	v_pk_add_f32 v[50:51], v[66:67], v[50:51]
	v_pk_add_f32 v[60:61], v[150:151], v[60:61]
	v_pk_add_f32 v[52:53], v[68:69], v[52:53]
	v_pk_add_f32 v[48:49], v[50:51], v[48:49]
	v_pk_add_f32 v[50:51], v[70:71], v[54:55]
	v_pk_add_f32 v[52:53], v[52:53], v[60:61]
	v_pk_add_f32 v[60:61], v[136:137], v[78:79]
	v_pk_add_f32 v[48:49], v[50:51], v[48:49]
	v_pk_add_f32 v[50:51], v[72:73], v[56:57]
	v_pk_add_f32 v[52:53], v[60:61], v[52:53]
	v_pk_add_f32 v[58:59], v[74:75], v[58:59]
	v_pk_add_f32 v[152:153], v[50:51], v[48:49]
	v_pk_add_f32 v[150:151], v[58:59], v[52:53]
	s_waitcnt lgkmcnt(0)
	s_barrier
	ds_read_b128 v[48:51], v169
	ds_read_b128 v[52:55], v169 offset:32
	ds_read_b128 v[116:119], v169 offset:6656
	ds_read_b128 v[120:123], v169 offset:6688
	s_waitcnt lgkmcnt(3)
	v_mfma_f32_32x32x16_bf16 v[64:79], v[48:51], v[100:103], v[32:47]
	ds_read_b128 v[124:127], v169 offset:64
	ds_read_b128 v[128:131], v169 offset:96
	ds_read_b128 v[132:135], v169 offset:6720
	ds_read_b128 v[136:139], v169 offset:6752
	s_waitcnt lgkmcnt(4)
	v_mfma_f32_32x32x16_bf16 v[64:79], v[52:55], v[96:99], v[64:79]
	v_mfma_f32_32x32x16_bf16 v[48:63], v[116:119], v[100:103], v[32:47]
	v_mfma_f32_32x32x16_bf16 v[48:63], v[120:123], v[96:99], v[48:63]
	s_waitcnt lgkmcnt(1)
	v_mfma_f32_32x32x16_bf16 v[64:79], v[124:127], v[92:95], v[64:79]
	v_mfma_f32_32x32x16_bf16 v[48:63], v[132:135], v[92:95], v[48:63]
	v_mfma_f32_32x32x16_bf16 v[64:79], v[128:131], v[88:91], v[64:79]
	ds_read_b128 v[116:119], v169 offset:128
	ds_read_b128 v[120:123], v169 offset:160
	ds_read_b128 v[128:131], v169 offset:6784
	ds_read_b128 v[176:179], v169 offset:6816
	s_waitcnt lgkmcnt(3)
	v_mfma_f32_32x32x16_bf16 v[48:63], v[136:139], v[88:91], v[48:63]
	v_mfma_f32_32x32x16_bf16 v[64:79], v[116:119], v[84:87], v[64:79]
	ds_read_b128 v[136:139], v170 offset:26624
	ds_read_b128 v[124:127], v170 offset:26656
	s_waitcnt lgkmcnt(3)
	v_mfma_f32_32x32x16_bf16 v[48:63], v[128:131], v[84:87], v[48:63]
	v_mfma_f32_32x32x16_bf16 v[64:79], v[120:123], v[80:83], v[64:79]
	ds_read_b128 v[132:135], v170 offset:26688
	ds_read_b128 v[120:123], v170 offset:26720
	ds_read_b128 v[144:147], v170 offset:31232
	ds_read_b128 v[140:143], v170 offset:31264
	ds_read_b128 v[128:131], v170 offset:31296
	ds_read_b128 v[116:119], v170 offset:31328
	s_waitcnt lgkmcnt(8)
	v_mfma_f32_32x32x16_bf16 v[48:63], v[176:179], v[80:83], v[48:63]
	s_add_i32 s43, s43, 1
	s_nop 10
	v_max_f32_e32 v148, v64, v48
	v_max_f32_e32 v160, v65, v49
	v_max_f32_e32 v161, v67, v51
	v_max3_f32 v176, v66, v50, v70
	v_max3_f32 v161, v161, v71, v55
	v_max3_f32 v148, v148, v68, v52
	v_max3_f32 v160, v160, v69, v53
	v_max3_f32 v176, v176, v54, v74
	v_max3_f32 v161, v161, v75, v59
	v_max3_f32 v148, v148, v72, v56
	v_max3_f32 v160, v160, v73, v57
	v_max3_f32 v176, v176, v58, v78
	v_max3_f32 v161, v161, v79, v63
	v_max3_f32 v148, v148, v76, v60
	v_max3_f32 v160, v160, v77, v61
	v_max3_f32 v161, v176, v62, v161
	v_max3_f32 v148, v148, v160, v161
	v_cmp_lt_f32_e32 vcc, s59, v148
	s_cbranch_vccz .Lmla_nr_0
	v_mov_b32_e32 v160, v148
	s_nop 1
	v_permlane32_swap_b32_e32 v148, v160
	v_max_f32_e32 v148, v148, v160
	v_max_f32_e32 v32, v148, v148
	v_max_f32_e32 v148, 0, v32
	v_exp_f32_e64 v160, -v148
	v_add_f32_e32 v168, v168, v148
	v_xor_b32_e32 v32, 0x80000000, v168
	v_mov_b32_e32 v33, v32
	v_mov_b32_e32 v34, v32
	v_mov_b32_e32 v35, v32
	v_mov_b32_e32 v36, v32
	v_mov_b32_e32 v37, v32
	v_mov_b32_e32 v38, v32
	v_mov_b32_e32 v39, v32
	v_mov_b32_e32 v40, v32
	v_mov_b32_e32 v41, v32
	v_mov_b32_e32 v42, v32
	v_mov_b32_e32 v43, v32
	v_mov_b32_e32 v44, v32
	v_mov_b32_e32 v45, v32
	v_mov_b32_e32 v46, v32
	v_mov_b32_e32 v47, v32
	v_pk_add_f32 v[64:65], v[64:65], v[148:149] op_sel_hi:[1,0] neg_lo:[0,1] neg_hi:[0,1]
	v_pk_add_f32 v[48:49], v[48:49], v[148:149] op_sel_hi:[1,0] neg_lo:[0,1] neg_hi:[0,1]
	v_pk_add_f32 v[66:67], v[66:67], v[148:149] op_sel_hi:[1,0] neg_lo:[0,1] neg_hi:[0,1]
	v_pk_add_f32 v[50:51], v[50:51], v[148:149] op_sel_hi:[1,0] neg_lo:[0,1] neg_hi:[0,1]
	v_pk_add_f32 v[68:69], v[68:69], v[148:149] op_sel_hi:[1,0] neg_lo:[0,1] neg_hi:[0,1]
	v_pk_add_f32 v[52:53], v[52:53], v[148:149] op_sel_hi:[1,0] neg_lo:[0,1] neg_hi:[0,1]
	v_pk_add_f32 v[70:71], v[70:71], v[148:149] op_sel_hi:[1,0] neg_lo:[0,1] neg_hi:[0,1]
	v_pk_add_f32 v[54:55], v[54:55], v[148:149] op_sel_hi:[1,0] neg_lo:[0,1] neg_hi:[0,1]
	v_pk_add_f32 v[72:73], v[72:73], v[148:149] op_sel_hi:[1,0] neg_lo:[0,1] neg_hi:[0,1]
	v_pk_add_f32 v[56:57], v[56:57], v[148:149] op_sel_hi:[1,0] neg_lo:[0,1] neg_hi:[0,1]
	v_pk_add_f32 v[74:75], v[74:75], v[148:149] op_sel_hi:[1,0] neg_lo:[0,1] neg_hi:[0,1]
	v_pk_add_f32 v[58:59], v[58:59], v[148:149] op_sel_hi:[1,0] neg_lo:[0,1] neg_hi:[0,1]
	v_pk_add_f32 v[76:77], v[76:77], v[148:149] op_sel_hi:[1,0] neg_lo:[0,1] neg_hi:[0,1]
	v_pk_add_f32 v[60:61], v[60:61], v[148:149] op_sel_hi:[1,0] neg_lo:[0,1] neg_hi:[0,1]
	v_pk_add_f32 v[78:79], v[78:79], v[148:149] op_sel_hi:[1,0] neg_lo:[0,1] neg_hi:[0,1]
	v_pk_add_f32 v[62:63], v[62:63], v[148:149] op_sel_hi:[1,0] neg_lo:[0,1] neg_hi:[0,1]
	v_pk_mul_f32 v[30:31], v[30:31], v[160:161] op_sel_hi:[1,0]
	v_pk_mul_f32 v[28:29], v[28:29], v[160:161] op_sel_hi:[1,0]
	v_pk_mul_f32 v[26:27], v[26:27], v[160:161] op_sel_hi:[1,0]
	v_pk_mul_f32 v[24:25], v[24:25], v[160:161] op_sel_hi:[1,0]
	v_pk_mul_f32 v[22:23], v[22:23], v[160:161] op_sel_hi:[1,0]
	v_pk_mul_f32 v[20:21], v[20:21], v[160:161] op_sel_hi:[1,0]
	v_pk_mul_f32 v[18:19], v[18:19], v[160:161] op_sel_hi:[1,0]
	v_pk_mul_f32 v[16:17], v[16:17], v[160:161] op_sel_hi:[1,0]
	v_pk_mul_f32 v[14:15], v[14:15], v[160:161] op_sel_hi:[1,0]
	v_pk_mul_f32 v[12:13], v[12:13], v[160:161] op_sel_hi:[1,0]
	v_pk_mul_f32 v[10:11], v[10:11], v[160:161] op_sel_hi:[1,0]
	v_pk_mul_f32 v[8:9], v[8:9], v[160:161] op_sel_hi:[1,0]
	v_pk_mul_f32 v[6:7], v[6:7], v[160:161] op_sel_hi:[1,0]
	v_pk_mul_f32 v[4:5], v[4:5], v[160:161] op_sel_hi:[1,0]
	v_pk_mul_f32 v[2:3], v[2:3], v[160:161] op_sel_hi:[1,0]
	v_pk_mul_f32 v[0:1], v[0:1], v[160:161] op_sel_hi:[1,0]
	v_pk_mul_f32 v[152:153], v[152:153], v[160:161] op_sel_hi:[1,0]
	v_pk_mul_f32 v[150:151], v[150:151], v[160:161] op_sel_hi:[1,0]
; #define AT_QK_LD0(kb_) do { if constexpr (NEGM) { const LAS unsigned char* kbp_ = Kl + (kb_) * KBUF + r32 * KROWB + hi * 16; AT_KLD2(0); __builtin_amdgcn_sched_barrier(0); } } while (0)
; template <int DQK, int DV, int RH, bool NEGM> ...
;     ...
;     const int NT = nkv / 64;
;     AT_GLOAD(0); AT_LSTORE(0, 0); __syncthreads();
;     int vs_prev = 2, vs_cur = 0, vs_next = 1;
;     if (!grpB) {
;         for (int t = 0; t < NT; ++t) {
;             const int kb = t & 1;
;             if (t + 1 < NT) AT_GLOAD(t + 1);
;             f32x16 p[RH][2];
;             AT_QK_LD0(kb); AT_QK(kb); AT_VLOAD(vs_cur); AT_SOFTMAX(); AT_PV(vs_cur);
;             if (t + 1 < NT) AT_LSTORE(kb ^ 1, vs_next);
.Lmla_nr_0:
	v_exp_f32_e32 v160, v64
	v_exp_f32_e32 v161, v65
	v_exp_f32_e32 v64, v66
	v_exp_f32_e32 v65, v67
	v_exp_f32_e32 v68, v68
	v_exp_f32_e32 v69, v69
	v_exp_f32_e32 v66, v70
	v_exp_f32_e32 v67, v71
	v_cvt_pk_bf16_f32 v176, v160, v161
	v_cvt_pk_bf16_f32 v177, v64, v65
	v_cvt_pk_bf16_f32 v178, v68, v69
	v_cvt_pk_bf16_f32 v179, v66, v67
	v_exp_f32_e32 v70, v74
	v_exp_f32_e32 v71, v75
	s_waitcnt lgkmcnt(0)
	v_mfma_f32_32x32x16_bf16 v[16:31], v[136:139], v[176:179], v[16:31]
	v_exp_f32_e32 v136, v72
	v_exp_f32_e32 v137, v73
	v_exp_f32_e32 v74, v76
	v_exp_f32_e32 v75, v77
	v_exp_f32_e32 v72, v78
	v_exp_f32_e32 v73, v79
	v_exp_f32_e32 v76, v48
	v_mfma_f32_32x32x16_bf16 v[0:15], v[144:147], v[176:179], v[0:15]
	v_cvt_pk_bf16_f32 v144, v136, v137
	v_cvt_pk_bf16_f32 v145, v70, v71
	v_cvt_pk_bf16_f32 v146, v74, v75
	v_cvt_pk_bf16_f32 v147, v72, v73
	v_exp_f32_e32 v77, v49
	v_exp_f32_e32 v48, v50
	v_exp_f32_e32 v49, v51
	v_mfma_f32_32x32x16_bf16 v[16:31], v[124:127], v[144:147], v[16:31]
	v_exp_f32_e32 v52, v52
	v_exp_f32_e32 v53, v53
	v_exp_f32_e32 v50, v54
	v_exp_f32_e32 v51, v55
	v_cvt_pk_bf16_f32 v124, v76, v77
	v_cvt_pk_bf16_f32 v125, v48, v49
	v_cvt_pk_bf16_f32 v126, v52, v53
	v_mfma_f32_32x32x16_bf16 v[0:15], v[140:143], v[144:147], v[0:15]
	v_cvt_pk_bf16_f32 v127, v50, v51
	v_exp_f32_e32 v78, v56
	v_exp_f32_e32 v79, v57
	v_exp_f32_e32 v54, v58
	v_exp_f32_e32 v55, v59
	v_exp_f32_e32 v58, v60
	v_exp_f32_e32 v59, v61
	v_mfma_f32_32x32x16_bf16 v[16:31], v[132:135], v[124:127], v[16:31]
	v_exp_f32_e32 v56, v62
	v_exp_f32_e32 v57, v63
	v_cvt_pk_bf16_f32 v60, v78, v79
	v_cvt_pk_bf16_f32 v61, v54, v55
	v_cvt_pk_bf16_f32 v62, v58, v59
	v_cvt_pk_bf16_f32 v63, v56, v57
	v_mfma_f32_32x32x16_bf16 v[0:15], v[128:131], v[124:127], v[0:15]
	v_mfma_f32_32x32x16_bf16 v[16:31], v[120:123], v[60:63], v[16:31]
	v_mfma_f32_32x32x16_bf16 v[0:15], v[116:119], v[60:63], v[0:15]
	s_waitcnt vmcnt(1)
	ds_write_b128 v249, v[104:107]
	s_mov_b64 exec, s[8:9]
	ds_write_b128 v250, v[108:111]
	s_mov_b64 exec, -1
	s_waitcnt vmcnt(0)
	ds_write2_b64 v247, v[112:113], v[114:115] offset1:2
	global_load_dwordx4 v[104:107], v154, s[98:99]
	s_mov_b64 exec, s[8:9]
	global_load_dwordx4 v[108:111], v156, s[98:99]
	s_mov_b64 exec, -1
	global_load_dwordx4 v[112:115], v158, s[100:101]
	s_add_u32 s98, s98, 0x18000
	s_addc_u32 s99, s99, 0
	s_add_u32 s100, s100, 0x80
	s_addc_u32 s101, s101, 0
	v_pk_add_f32 v[48:49], v[64:65], v[48:49]
	v_pk_add_f32 v[60:61], v[160:161], v[76:77]
	v_pk_add_f32 v[48:49], v[152:153], v[48:49]
	v_pk_add_f32 v[50:51], v[66:67], v[50:51]
	v_pk_add_f32 v[60:61], v[150:151], v[60:61]
	v_pk_add_f32 v[52:53], v[68:69], v[52:53]
	v_pk_add_f32 v[48:49], v[50:51], v[48:49]
	v_pk_add_f32 v[50:51], v[70:71], v[54:55]
	v_pk_add_f32 v[52:53], v[52:53], v[60:61]
	v_pk_add_f32 v[60:61], v[136:137], v[78:79]
	v_pk_add_f32 v[48:49], v[50:51], v[48:49]
	v_pk_add_f32 v[50:51], v[72:73], v[56:57]
	v_pk_add_f32 v[52:53], v[60:61], v[52:53]
	v_pk_add_f32 v[58:59], v[74:75], v[58:59]
	v_pk_add_f32 v[152:153], v[50:51], v[48:49]
	v_pk_add_f32 v[150:151], v[58:59], v[52:53]
	ds_read_b128 v[48:51], v169 offset:13312
	ds_read_b128 v[52:55], v169 offset:13344
	ds_read_b128 v[116:119], v169 offset:19968
	ds_read_b128 v[120:123], v169 offset:20000
	s_waitcnt lgkmcnt(3)
	v_mfma_f32_32x32x16_bf16 v[64:79], v[48:51], v[100:103], v[32:47]
	ds_read_b128 v[124:127], v169 offset:13376
	ds_read_b128 v[128:131], v169 offset:13408
	ds_read_b128 v[132:135], v169 offset:20032
	ds_read_b128 v[136:139], v169 offset:20064
	s_waitcnt lgkmcnt(4)
	v_mfma_f32_32x32x16_bf16 v[64:79], v[52:55], v[96:99], v[64:79]
	v_mfma_f32_32x32x16_bf16 v[48:63], v[116:119], v[100:103], v[32:47]
	v_mfma_f32_32x32x16_bf16 v[48:63], v[120:123], v[96:99], v[48:63]
	s_waitcnt lgkmcnt(1)
	v_mfma_f32_32x32x16_bf16 v[64:79], v[124:127], v[92:95], v[64:79]
	v_mfma_f32_32x32x16_bf16 v[48:63], v[132:135], v[92:95], v[48:63]
	v_mfma_f32_32x32x16_bf16 v[64:79], v[128:131], v[88:91], v[64:79]
	ds_read_b128 v[116:119], v169 offset:13440
	ds_read_b128 v[120:123], v169 offset:13472
	ds_read_b128 v[128:131], v169 offset:20096
	ds_read_b128 v[176:179], v169 offset:20128
	s_waitcnt lgkmcnt(3)
	v_mfma_f32_32x32x16_bf16 v[48:63], v[136:139], v[88:91], v[48:63]
	v_mfma_f32_32x32x16_bf16 v[64:79], v[116:119], v[84:87], v[64:79]
	ds_read_b128 v[136:139], v170 offset:35840
	ds_read_b128 v[124:127], v170 offset:35872
	s_waitcnt lgkmcnt(3)
	v_mfma_f32_32x32x16_bf16 v[48:63], v[128:131], v[84:87], v[48:63]
	v_mfma_f32_32x32x16_bf16 v[64:79], v[120:123], v[80:83], v[64:79]
	ds_read_b128 v[132:135], v170 offset:35904
	ds_read_b128 v[120:123], v170 offset:35936
	ds_read_b128 v[144:147], v170 offset:40448
	ds_read_b128 v[140:143], v170 offset:40480
	ds_read_b128 v[128:131], v170 offset:40512
	ds_read_b128 v[116:119], v170 offset:40544
	s_waitcnt lgkmcnt(8)
	v_mfma_f32_32x32x16_bf16 v[48:63], v[176:179], v[80:83], v[48:63]
	s_add_i32 s43, s43, 1
	s_nop 10
	v_max_f32_e32 v148, v64, v48
	v_max_f32_e32 v160, v65, v49
	v_max_f32_e32 v161, v67, v51
	v_max3_f32 v176, v66, v50, v70
	v_max3_f32 v161, v161, v71, v55
	v_max3_f32 v148, v148, v68, v52
	v_max3_f32 v160, v160, v69, v53
	v_max3_f32 v176, v176, v54, v74
	v_max3_f32 v161, v161, v75, v59
	v_max3_f32 v148, v148, v72, v56
	v_max3_f32 v160, v160, v73, v57
	v_max3_f32 v176, v176, v58, v78
	v_max3_f32 v161, v161, v79, v63
	v_max3_f32 v148, v148, v76, v60
	v_max3_f32 v160, v160, v77, v61
	v_max3_f32 v161, v176, v62, v161
	v_max3_f32 v148, v148, v160, v161
	v_cmp_lt_f32_e32 vcc, s59, v148
	s_cbranch_vccz .Lmla_nr_1
; #define AT_QK_LD0(kb_) do { if constexpr (NEGM) { const LAS unsigned char* kbp_ = Kl + (kb_) * KBUF + r32 * KROWB + hi * 16; AT_KLD2(0); __builtin_amdgcn_sched_barrier(0); } } while (0)
; template <int DQK, int DV, int RH, bool NEGM> ...
;     ...
;     const int NT = nkv / 64;
;     AT_GLOAD(0); AT_LSTORE(0, 0); __syncthreads();
;     int vs_prev = 2, vs_cur = 0, vs_next = 1;
;     if (!grpB) {
;         for (int t = 0; t < NT; ++t) {
;             const int kb = t & 1;
;             if (t + 1 < NT) AT_GLOAD(t + 1);
;             f32x16 p[RH][2];
;             AT_QK_LD0(kb); AT_QK(kb); AT_VLOAD(vs_cur); AT_SOFTMAX(); AT_PV(vs_cur);
;             if (t + 1 < NT) AT_LSTORE(kb ^ 1, vs_next);
	v_mov_b32_e32 v160, v148
	s_nop 1
	v_permlane32_swap_b32_e32 v148, v160
	v_max_f32_e32 v148, v148, v160
	v_max_f32_e32 v32, v148, v148
	v_max_f32_e32 v148, 0, v32
	v_exp_f32_e64 v160, -v148
	v_add_f32_e32 v168, v168, v148
	v_xor_b32_e32 v32, 0x80000000, v168
	v_mov_b32_e32 v33, v32
	v_mov_b32_e32 v34, v32
	v_mov_b32_e32 v35, v32
	v_mov_b32_e32 v36, v32
	v_mov_b32_e32 v37, v32
	v_mov_b32_e32 v38, v32
	v_mov_b32_e32 v39, v32
	v_mov_b32_e32 v40, v32
	v_mov_b32_e32 v41, v32
	v_mov_b32_e32 v42, v32
	v_mov_b32_e32 v43, v32
	v_mov_b32_e32 v44, v32
	v_mov_b32_e32 v45, v32
	v_mov_b32_e32 v46, v32
	v_mov_b32_e32 v47, v32
	v_pk_add_f32 v[64:65], v[64:65], v[148:149] op_sel_hi:[1,0] neg_lo:[0,1] neg_hi:[0,1]
	v_pk_add_f32 v[48:49], v[48:49], v[148:149] op_sel_hi:[1,0] neg_lo:[0,1] neg_hi:[0,1]
	v_pk_add_f32 v[66:67], v[66:67], v[148:149] op_sel_hi:[1,0] neg_lo:[0,1] neg_hi:[0,1]
	v_pk_add_f32 v[50:51], v[50:51], v[148:149] op_sel_hi:[1,0] neg_lo:[0,1] neg_hi:[0,1]
	v_pk_add_f32 v[68:69], v[68:69], v[148:149] op_sel_hi:[1,0] neg_lo:[0,1] neg_hi:[0,1]
	v_pk_add_f32 v[52:53], v[52:53], v[148:149] op_sel_hi:[1,0] neg_lo:[0,1] neg_hi:[0,1]
	v_pk_add_f32 v[70:71], v[70:71], v[148:149] op_sel_hi:[1,0] neg_lo:[0,1] neg_hi:[0,1]
	v_pk_add_f32 v[54:55], v[54:55], v[148:149] op_sel_hi:[1,0] neg_lo:[0,1] neg_hi:[0,1]
	v_pk_add_f32 v[72:73], v[72:73], v[148:149] op_sel_hi:[1,0] neg_lo:[0,1] neg_hi:[0,1]
	v_pk_add_f32 v[56:57], v[56:57], v[148:149] op_sel_hi:[1,0] neg_lo:[0,1] neg_hi:[0,1]
	v_pk_add_f32 v[74:75], v[74:75], v[148:149] op_sel_hi:[1,0] neg_lo:[0,1] neg_hi:[0,1]
	v_pk_add_f32 v[58:59], v[58:59], v[148:149] op_sel_hi:[1,0] neg_lo:[0,1] neg_hi:[0,1]
	v_pk_add_f32 v[76:77], v[76:77], v[148:149] op_sel_hi:[1,0] neg_lo:[0,1] neg_hi:[0,1]
	v_pk_add_f32 v[60:61], v[60:61], v[148:149] op_sel_hi:[1,0] neg_lo:[0,1] neg_hi:[0,1]
	v_pk_add_f32 v[78:79], v[78:79], v[148:149] op_sel_hi:[1,0] neg_lo:[0,1] neg_hi:[0,1]
	v_pk_add_f32 v[62:63], v[62:63], v[148:149] op_sel_hi:[1,0] neg_lo:[0,1] neg_hi:[0,1]
	v_pk_mul_f32 v[30:31], v[30:31], v[160:161] op_sel_hi:[1,0]
	v_pk_mul_f32 v[28:29], v[28:29], v[160:161] op_sel_hi:[1,0]
	v_pk_mul_f32 v[26:27], v[26:27], v[160:161] op_sel_hi:[1,0]
	v_pk_mul_f32 v[24:25], v[24:25], v[160:161] op_sel_hi:[1,0]
	v_pk_mul_f32 v[22:23], v[22:23], v[160:161] op_sel_hi:[1,0]
	v_pk_mul_f32 v[20:21], v[20:21], v[160:161] op_sel_hi:[1,0]
	v_pk_mul_f32 v[18:19], v[18:19], v[160:161] op_sel_hi:[1,0]
	v_pk_mul_f32 v[16:17], v[16:17], v[160:161] op_sel_hi:[1,0]
	v_pk_mul_f32 v[14:15], v[14:15], v[160:161] op_sel_hi:[1,0]
	v_pk_mul_f32 v[12:13], v[12:13], v[160:161] op_sel_hi:[1,0]
	v_pk_mul_f32 v[10:11], v[10:11], v[160:161] op_sel_hi:[1,0]
	v_pk_mul_f32 v[8:9], v[8:9], v[160:161] op_sel_hi:[1,0]
	v_pk_mul_f32 v[6:7], v[6:7], v[160:161] op_sel_hi:[1,0]
	v_pk_mul_f32 v[4:5], v[4:5], v[160:161] op_sel_hi:[1,0]
	v_pk_mul_f32 v[2:3], v[2:3], v[160:161] op_sel_hi:[1,0]
	v_pk_mul_f32 v[0:1], v[0:1], v[160:161] op_sel_hi:[1,0]
	v_pk_mul_f32 v[152:153], v[152:153], v[160:161] op_sel_hi:[1,0]
	v_pk_mul_f32 v[150:151], v[150:151], v[160:161] op_sel_hi:[1,0]
.Lmla_nr_1:
	v_exp_f32_e32 v160, v64
	v_exp_f32_e32 v161, v65
	v_exp_f32_e32 v64, v66
	v_exp_f32_e32 v65, v67
	v_exp_f32_e32 v68, v68
	v_exp_f32_e32 v69, v69
	v_exp_f32_e32 v66, v70
	v_exp_f32_e32 v67, v71
	v_cvt_pk_bf16_f32 v176, v160, v161
	v_cvt_pk_bf16_f32 v177, v64, v65
	v_cvt_pk_bf16_f32 v178, v68, v69
	v_cvt_pk_bf16_f32 v179, v66, v67
	v_exp_f32_e32 v70, v74
	v_exp_f32_e32 v71, v75
	s_waitcnt lgkmcnt(0)
	v_mfma_f32_32x32x16_bf16 v[16:31], v[136:139], v[176:179], v[16:31]
	v_exp_f32_e32 v136, v72
	v_exp_f32_e32 v137, v73
	v_exp_f32_e32 v74, v76
	v_exp_f32_e32 v75, v77
	v_exp_f32_e32 v72, v78
	v_exp_f32_e32 v73, v79
	v_exp_f32_e32 v76, v48
	v_mfma_f32_32x32x16_bf16 v[0:15], v[144:147], v[176:179], v[0:15]
	v_cvt_pk_bf16_f32 v144, v136, v137
	v_cvt_pk_bf16_f32 v145, v70, v71
	v_cvt_pk_bf16_f32 v146, v74, v75
	v_cvt_pk_bf16_f32 v147, v72, v73
	v_exp_f32_e32 v77, v49
	v_exp_f32_e32 v48, v50
	v_exp_f32_e32 v49, v51
	v_mfma_f32_32x32x16_bf16 v[16:31], v[124:127], v[144:147], v[16:31]
	v_exp_f32_e32 v52, v52
	v_exp_f32_e32 v53, v53
	v_exp_f32_e32 v50, v54
	v_exp_f32_e32 v51, v55
	v_cvt_pk_bf16_f32 v124, v76, v77
	v_cvt_pk_bf16_f32 v125, v48, v49
	v_cvt_pk_bf16_f32 v126, v52, v53
	v_mfma_f32_32x32x16_bf16 v[0:15], v[140:143], v[144:147], v[0:15]
	v_cvt_pk_bf16_f32 v127, v50, v51
	v_exp_f32_e32 v78, v56
	v_exp_f32_e32 v79, v57
	v_exp_f32_e32 v54, v58
	v_exp_f32_e32 v55, v59
	v_exp_f32_e32 v58, v60
	v_exp_f32_e32 v59, v61
	v_mfma_f32_32x32x16_bf16 v[16:31], v[132:135], v[124:127], v[16:31]
	v_exp_f32_e32 v56, v62
	v_exp_f32_e32 v57, v63
	v_cvt_pk_bf16_f32 v60, v78, v79
	v_cvt_pk_bf16_f32 v61, v54, v55
	v_cvt_pk_bf16_f32 v62, v58, v59
	v_cvt_pk_bf16_f32 v63, v56, v57
	v_mfma_f32_32x32x16_bf16 v[0:15], v[128:131], v[124:127], v[0:15]
	v_mfma_f32_32x32x16_bf16 v[16:31], v[120:123], v[60:63], v[16:31]
	v_mfma_f32_32x32x16_bf16 v[0:15], v[116:119], v[60:63], v[0:15]
	s_waitcnt vmcnt(1)
	ds_write_b128 v249, v[104:107] offset:13312
	s_mov_b64 exec, s[8:9]
	ds_write_b128 v250, v[108:111] offset:13312
	s_mov_b64 exec, -1
	s_waitcnt vmcnt(0)
	ds_write2_b64 v248, v[112:113], v[114:115] offset1:2
	s_cmp_eq_u32 s43, 62
	s_cbranch_scc1 .Lmla_noload
	global_load_dwordx4 v[104:107], v154, s[98:99]
	s_mov_b64 exec, s[8:9]
	global_load_dwordx4 v[108:111], v156, s[98:99]
	s_mov_b64 exec, -1
	global_load_dwordx4 v[112:115], v158, s[100:101]
	s_add_u32 s98, s98, 0x18000
	s_addc_u32 s99, s99, 0
	s_add_u32 s100, s100, 0x80
	s_addc_u32 s101, s101, 0
; #define AT_QK_LD0(kb_) do { if constexpr (NEGM) { const LAS unsigned char* kbp_ = Kl + (kb_) * KBUF + r32 * KROWB + hi * 16; AT_KLD2(0); __builtin_amdgcn_sched_barrier(0); } } while (0)
; template <int DQK, int DV, int RH, bool NEGM> ...
;     ...
;             if (t + 1 < NT) AT_GLOAD(t + 1);
;             f32x16 p[RH][2];
;             AT_QK_LD0(kb); AT_QK(kb); AT_VLOAD(vs_cur); AT_SOFTMAX(); AT_PV(vs_cur);
;             if (t + 1 < NT) AT_LSTORE(kb ^ 1, vs_next);
;             __syncthreads();
;             vs_prev = vs_cur; vs_cur = vs_next; vs_next = (vs_next == 2) ? 0 : vs_next + 1;
.Lmla_noload:
	v_pk_add_f32 v[48:49], v[64:65], v[48:49]
	v_pk_add_f32 v[60:61], v[160:161], v[76:77]
	v_pk_add_f32 v[48:49], v[152:153], v[48:49]
	v_pk_add_f32 v[50:51], v[66:67], v[50:51]
	v_pk_add_f32 v[60:61], v[150:151], v[60:61]
	v_pk_add_f32 v[52:53], v[68:69], v[52:53]
	v_pk_add_f32 v[48:49], v[50:51], v[48:49]
	v_pk_add_f32 v[50:51], v[70:71], v[54:55]
	v_pk_add_f32 v[52:53], v[52:53], v[60:61]
	v_pk_add_f32 v[60:61], v[136:137], v[78:79]
	v_pk_add_f32 v[48:49], v[50:51], v[48:49]
	v_pk_add_f32 v[50:51], v[72:73], v[56:57]
	v_pk_add_f32 v[52:53], v[60:61], v[52:53]
	v_pk_add_f32 v[58:59], v[74:75], v[58:59]
	v_pk_add_f32 v[152:153], v[50:51], v[48:49]
	v_pk_add_f32 v[150:151], v[58:59], v[52:53]
	s_cmp_lg_u32 s43, 62
	s_waitcnt lgkmcnt(0)
	s_barrier
	s_cbranch_scc1 .Lmla_loop
	ds_read_b128 v[48:51], v251
	ds_read_b128 v[52:55], v251 offset:32
	ds_read_b128 v[116:119], v251 offset:6656
	ds_read_b128 v[120:123], v251 offset:6688
	s_waitcnt lgkmcnt(3)
	v_mfma_f32_32x32x16_bf16 v[64:79], v[48:51], v[100:103], v[32:47]
	ds_read_b128 v[124:127], v251 offset:64
	ds_read_b128 v[128:131], v251 offset:96
	ds_read_b128 v[132:135], v251 offset:6720
	ds_read_b128 v[136:139], v251 offset:6752
	s_waitcnt lgkmcnt(4)
	v_mfma_f32_32x32x16_bf16 v[64:79], v[52:55], v[96:99], v[64:79]
	v_mfma_f32_32x32x16_bf16 v[48:63], v[116:119], v[100:103], v[32:47]
	v_mfma_f32_32x32x16_bf16 v[48:63], v[120:123], v[96:99], v[48:63]
	s_waitcnt lgkmcnt(1)
	v_mfma_f32_32x32x16_bf16 v[64:79], v[124:127], v[92:95], v[64:79]
	v_mfma_f32_32x32x16_bf16 v[48:63], v[132:135], v[92:95], v[48:63]
	v_mfma_f32_32x32x16_bf16 v[64:79], v[128:131], v[88:91], v[64:79]
	ds_read_b128 v[116:119], v251 offset:128
	ds_read_b128 v[120:123], v251 offset:160
	ds_read_b128 v[128:131], v251 offset:6784
	ds_read_b128 v[176:179], v251 offset:6816
	s_waitcnt lgkmcnt(3)
	v_mfma_f32_32x32x16_bf16 v[48:63], v[136:139], v[88:91], v[48:63]
	v_mfma_f32_32x32x16_bf16 v[64:79], v[116:119], v[84:87], v[64:79]
	ds_read_b128 v[136:139], v170 offset:45056
	ds_read_b128 v[124:127], v170 offset:45088
	s_waitcnt lgkmcnt(3)
	v_mfma_f32_32x32x16_bf16 v[48:63], v[128:131], v[84:87], v[48:63]
	v_mfma_f32_32x32x16_bf16 v[64:79], v[120:123], v[80:83], v[64:79]
	ds_read_b128 v[132:135], v170 offset:45120
	ds_read_b128 v[120:123], v170 offset:45152
	ds_read_b128 v[144:147], v170 offset:49664
	ds_read_b128 v[140:143], v170 offset:49696
	ds_read_b128 v[128:131], v170 offset:49728
	ds_read_b128 v[116:119], v170 offset:49760
	s_waitcnt lgkmcnt(8)
	v_mfma_f32_32x32x16_bf16 v[48:63], v[176:179], v[80:83], v[48:63]
	s_add_i32 s43, s43, 1
	s_nop 10
	v_max_f32_e32 v148, v64, v48
	v_max_f32_e32 v160, v65, v49
	v_max_f32_e32 v161, v67, v51
	v_max3_f32 v176, v66, v50, v70
	v_max3_f32 v161, v161, v71, v55
	v_max3_f32 v148, v148, v68, v52
	v_max3_f32 v160, v160, v69, v53
	v_max3_f32 v176, v176, v54, v74
	v_max3_f32 v161, v161, v75, v59
	v_max3_f32 v148, v148, v72, v56
	v_max3_f32 v160, v160, v73, v57
	v_max3_f32 v176, v176, v58, v78
	v_max3_f32 v161, v161, v79, v63
	v_max3_f32 v148, v148, v76, v60
	v_max3_f32 v160, v160, v77, v61
	v_max3_f32 v161, v176, v62, v161
	v_max3_f32 v148, v148, v160, v161
	v_cmp_lt_f32_e32 vcc, s59, v148
	s_cbranch_vccz .Lmla_nr_t
	v_mov_b32_e32 v160, v148
	s_nop 1
	v_permlane32_swap_b32_e32 v148, v160
	v_max_f32_e32 v148, v148, v160
	v_max_f32_e32 v32, v148, v148
	v_max_f32_e32 v148, 0, v32
	v_exp_f32_e64 v160, -v148
	v_add_f32_e32 v168, v168, v148
	v_xor_b32_e32 v32, 0x80000000, v168
	v_mov_b32_e32 v33, v32
	v_mov_b32_e32 v34, v32
	v_mov_b32_e32 v35, v32
	v_mov_b32_e32 v36, v32
	v_mov_b32_e32 v37, v32
	v_mov_b32_e32 v38, v32
	v_mov_b32_e32 v39, v32
	v_mov_b32_e32 v40, v32
	v_mov_b32_e32 v41, v32
	v_mov_b32_e32 v42, v32
	v_mov_b32_e32 v43, v32
	v_mov_b32_e32 v44, v32
	v_mov_b32_e32 v45, v32
	v_mov_b32_e32 v46, v32
	v_mov_b32_e32 v47, v32
	v_pk_add_f32 v[64:65], v[64:65], v[148:149] op_sel_hi:[1,0] neg_lo:[0,1] neg_hi:[0,1]
	v_pk_add_f32 v[48:49], v[48:49], v[148:149] op_sel_hi:[1,0] neg_lo:[0,1] neg_hi:[0,1]
	v_pk_add_f32 v[66:67], v[66:67], v[148:149] op_sel_hi:[1,0] neg_lo:[0,1] neg_hi:[0,1]
	v_pk_add_f32 v[50:51], v[50:51], v[148:149] op_sel_hi:[1,0] neg_lo:[0,1] neg_hi:[0,1]
	v_pk_add_f32 v[68:69], v[68:69], v[148:149] op_sel_hi:[1,0] neg_lo:[0,1] neg_hi:[0,1]
	v_pk_add_f32 v[52:53], v[52:53], v[148:149] op_sel_hi:[1,0] neg_lo:[0,1] neg_hi:[0,1]
	v_pk_add_f32 v[70:71], v[70:71], v[148:149] op_sel_hi:[1,0] neg_lo:[0,1] neg_hi:[0,1]
	v_pk_add_f32 v[54:55], v[54:55], v[148:149] op_sel_hi:[1,0] neg_lo:[0,1] neg_hi:[0,1]
	v_pk_add_f32 v[72:73], v[72:73], v[148:149] op_sel_hi:[1,0] neg_lo:[0,1] neg_hi:[0,1]
	v_pk_add_f32 v[56:57], v[56:57], v[148:149] op_sel_hi:[1,0] neg_lo:[0,1] neg_hi:[0,1]
	v_pk_add_f32 v[74:75], v[74:75], v[148:149] op_sel_hi:[1,0] neg_lo:[0,1] neg_hi:[0,1]
	v_pk_add_f32 v[58:59], v[58:59], v[148:149] op_sel_hi:[1,0] neg_lo:[0,1] neg_hi:[0,1]
	v_pk_add_f32 v[76:77], v[76:77], v[148:149] op_sel_hi:[1,0] neg_lo:[0,1] neg_hi:[0,1]
	v_pk_add_f32 v[60:61], v[60:61], v[148:149] op_sel_hi:[1,0] neg_lo:[0,1] neg_hi:[0,1]
	v_pk_add_f32 v[78:79], v[78:79], v[148:149] op_sel_hi:[1,0] neg_lo:[0,1] neg_hi:[0,1]
	v_pk_add_f32 v[62:63], v[62:63], v[148:149] op_sel_hi:[1,0] neg_lo:[0,1] neg_hi:[0,1]
	v_pk_mul_f32 v[30:31], v[30:31], v[160:161] op_sel_hi:[1,0]
	v_pk_mul_f32 v[28:29], v[28:29], v[160:161] op_sel_hi:[1,0]
	v_pk_mul_f32 v[26:27], v[26:27], v[160:161] op_sel_hi:[1,0]
	v_pk_mul_f32 v[24:25], v[24:25], v[160:161] op_sel_hi:[1,0]
	v_pk_mul_f32 v[22:23], v[22:23], v[160:161] op_sel_hi:[1,0]
	v_pk_mul_f32 v[20:21], v[20:21], v[160:161] op_sel_hi:[1,0]
	v_pk_mul_f32 v[18:19], v[18:19], v[160:161] op_sel_hi:[1,0]
	v_pk_mul_f32 v[16:17], v[16:17], v[160:161] op_sel_hi:[1,0]
	v_pk_mul_f32 v[14:15], v[14:15], v[160:161] op_sel_hi:[1,0]
	v_pk_mul_f32 v[12:13], v[12:13], v[160:161] op_sel_hi:[1,0]
	v_pk_mul_f32 v[10:11], v[10:11], v[160:161] op_sel_hi:[1,0]
	v_pk_mul_f32 v[8:9], v[8:9], v[160:161] op_sel_hi:[1,0]
	v_pk_mul_f32 v[6:7], v[6:7], v[160:161] op_sel_hi:[1,0]
	v_pk_mul_f32 v[4:5], v[4:5], v[160:161] op_sel_hi:[1,0]
	v_pk_mul_f32 v[2:3], v[2:3], v[160:161] op_sel_hi:[1,0]
	v_pk_mul_f32 v[0:1], v[0:1], v[160:161] op_sel_hi:[1,0]
	v_pk_mul_f32 v[152:153], v[152:153], v[160:161] op_sel_hi:[1,0]
	v_pk_mul_f32 v[150:151], v[150:151], v[160:161] op_sel_hi:[1,0]
.Lmla_nr_t:
	v_exp_f32_e32 v160, v64
	v_exp_f32_e32 v161, v65
	v_exp_f32_e32 v64, v66
	v_exp_f32_e32 v65, v67
	v_exp_f32_e32 v68, v68
	v_exp_f32_e32 v69, v69
	v_exp_f32_e32 v66, v70
	v_exp_f32_e32 v67, v71
	v_cvt_pk_bf16_f32 v176, v160, v161
	v_cvt_pk_bf16_f32 v177, v64, v65
	v_cvt_pk_bf16_f32 v178, v68, v69
	v_cvt_pk_bf16_f32 v179, v66, v67
	v_exp_f32_e32 v70, v74
	v_exp_f32_e32 v71, v75
	s_waitcnt lgkmcnt(0)
	v_mfma_f32_32x32x16_bf16 v[16:31], v[136:139], v[176:179], v[16:31]
	v_exp_f32_e32 v136, v72
	v_exp_f32_e32 v137, v73
	v_exp_f32_e32 v74, v76
	v_exp_f32_e32 v75, v77
	v_exp_f32_e32 v72, v78
	v_exp_f32_e32 v73, v79
	v_exp_f32_e32 v76, v48
	v_mfma_f32_32x32x16_bf16 v[0:15], v[144:147], v[176:179], v[0:15]
	v_cvt_pk_bf16_f32 v144, v136, v137
	v_cvt_pk_bf16_f32 v145, v70, v71
	v_cvt_pk_bf16_f32 v146, v74, v75
	v_cvt_pk_bf16_f32 v147, v72, v73
	v_exp_f32_e32 v77, v49
	v_exp_f32_e32 v48, v50
	v_exp_f32_e32 v49, v51
	v_mfma_f32_32x32x16_bf16 v[16:31], v[124:127], v[144:147], v[16:31]
	v_exp_f32_e32 v52, v52
	v_exp_f32_e32 v53, v53
	v_exp_f32_e32 v50, v54
	v_exp_f32_e32 v51, v55
	v_cvt_pk_bf16_f32 v124, v76, v77
	v_cvt_pk_bf16_f32 v125, v48, v49
	v_cvt_pk_bf16_f32 v126, v52, v53
	v_mfma_f32_32x32x16_bf16 v[0:15], v[140:143], v[144:147], v[0:15]
	v_cvt_pk_bf16_f32 v127, v50, v51
	v_exp_f32_e32 v78, v56
	v_exp_f32_e32 v79, v57
	v_exp_f32_e32 v54, v58
	v_exp_f32_e32 v55, v59
	v_exp_f32_e32 v58, v60
	v_exp_f32_e32 v59, v61
	v_mfma_f32_32x32x16_bf16 v[16:31], v[132:135], v[124:127], v[16:31]
	v_exp_f32_e32 v56, v62
	v_exp_f32_e32 v57, v63
	v_cvt_pk_bf16_f32 v60, v78, v79
	v_cvt_pk_bf16_f32 v61, v54, v55
	v_cvt_pk_bf16_f32 v62, v58, v59
	v_cvt_pk_bf16_f32 v63, v56, v57
	v_mfma_f32_32x32x16_bf16 v[0:15], v[128:131], v[124:127], v[0:15]
	v_mfma_f32_32x32x16_bf16 v[16:31], v[120:123], v[60:63], v[16:31]
	v_mfma_f32_32x32x16_bf16 v[0:15], v[116:119], v[60:63], v[0:15]
	v_pk_add_f32 v[48:49], v[64:65], v[48:49]
	v_pk_add_f32 v[60:61], v[160:161], v[76:77]
	v_pk_add_f32 v[48:49], v[152:153], v[48:49]
	v_pk_add_f32 v[50:51], v[66:67], v[50:51]
	v_pk_add_f32 v[60:61], v[150:151], v[60:61]
	v_pk_add_f32 v[52:53], v[68:69], v[52:53]
	v_pk_add_f32 v[48:49], v[50:51], v[48:49]
	v_pk_add_f32 v[50:51], v[70:71], v[54:55]
	v_pk_add_f32 v[52:53], v[52:53], v[60:61]
	v_pk_add_f32 v[60:61], v[136:137], v[78:79]
	v_pk_add_f32 v[48:49], v[50:51], v[48:49]
	v_pk_add_f32 v[50:51], v[72:73], v[56:57]
	v_pk_add_f32 v[52:53], v[60:61], v[52:53]
	v_pk_add_f32 v[58:59], v[74:75], v[58:59]
	v_pk_add_f32 v[152:153], v[50:51], v[48:49]
	v_pk_add_f32 v[150:151], v[58:59], v[52:53]
	s_mov_b32 s21, 0x6c00
	ds_read_b128 v[64:67], v251 offset:13312
	ds_read_b128 v[68:71], v251 offset:13344
	ds_read_b128 v[72:75], v251 offset:19968
	ds_read_b128 v[76:79], v251 offset:20000
	s_waitcnt lgkmcnt(3)
	v_mfma_f32_32x32x16_bf16 v[48:63], v[64:67], v[100:103], v[32:47]
	ds_read_b128 v[64:67], v251 offset:13376
	ds_read_b128 v[104:107], v251 offset:13408
	ds_read_b128 v[108:111], v251 offset:20032
	ds_read_b128 v[112:115], v251 offset:20064
	s_waitcnt lgkmcnt(6)
	v_mfma_f32_32x32x16_bf16 v[48:63], v[68:71], v[96:99], v[48:63]
	s_waitcnt lgkmcnt(5)
	v_mfma_f32_32x32x16_bf16 v[32:47], v[72:75], v[100:103], v[32:47]
	s_waitcnt lgkmcnt(4)
	v_mfma_f32_32x32x16_bf16 v[32:47], v[76:79], v[96:99], v[32:47]
	s_waitcnt lgkmcnt(3)
	v_mfma_f32_32x32x16_bf16 v[48:63], v[64:67], v[92:95], v[48:63]
	ds_read_b128 v[64:67], v251 offset:13440
	ds_read_b128 v[68:71], v251 offset:13472
	ds_read_b128 v[72:75], v251 offset:20096
	ds_read_b128 v[76:79], v251 offset:20128
	s_waitcnt lgkmcnt(5)
	v_mfma_f32_32x32x16_bf16 v[32:47], v[108:111], v[92:95], v[32:47]
	v_mfma_f32_32x32x16_bf16 v[48:63], v[104:107], v[88:91], v[48:63]
	s_waitcnt lgkmcnt(4)
	v_mfma_f32_32x32x16_bf16 v[32:47], v[112:115], v[88:91], v[32:47]
	s_waitcnt lgkmcnt(3)
	v_mfma_f32_32x32x16_bf16 v[48:63], v[64:67], v[84:87], v[48:63]
	v_add3_u32 v64, v167, s21, v173
	v_add_u32_e32 v65, 0x6800, v64
	ds_read_b128 v[108:111], v65
	ds_read_b128 v[104:107], v65 offset:32
	ds_read_b128 v[96:99], v65 offset:64
	ds_read_b128 v[88:91], v65 offset:96
	s_waitcnt lgkmcnt(5)
	v_mfma_f32_32x32x16_bf16 v[32:47], v[72:75], v[84:87], v[32:47]
	ds_read_b128 v[112:115], v65 offset:4608
	ds_read_b128 v[100:103], v65 offset:4640
	ds_read_b128 v[92:95], v65 offset:4672
	ds_read_b128 v[84:87], v65 offset:4704
	v_mfma_f32_32x32x16_bf16 v[48:63], v[68:71], v[80:83], v[48:63]
	s_waitcnt lgkmcnt(8)
	v_mfma_f32_32x32x16_bf16 v[32:47], v[76:79], v[80:83], v[32:47]
	s_nop 11
	v_max_f32_e32 v64, v32, v32
	v_max_f32_e32 v65, v48, v48
	v_max_f32_e32 v64, v65, v64
	v_max_f32_e32 v65, v33, v33
	v_max_f32_e32 v66, v49, v49
	v_max_f32_e32 v65, v66, v65
	v_max_f32_e32 v66, v35, v35
	v_max_f32_e32 v67, v51, v51
	v_max_f32_e32 v66, v67, v66
	v_max3_f32 v67, v50, v34, v54
	v_max3_f32 v66, v66, v55, v39
	v_max3_f32 v64, v64, v52, v36
	v_max3_f32 v65, v65, v53, v37
	v_max3_f32 v67, v67, v38, v58
	v_max3_f32 v66, v66, v59, v43
	v_max3_f32 v64, v64, v56, v40
	v_max3_f32 v65, v65, v57, v41
	v_max3_f32 v67, v67, v42, v62
	v_max3_f32 v66, v66, v63, v47
	v_max3_f32 v64, v64, v60, v44
	v_max3_f32 v65, v65, v61, v45
	v_max3_f32 v66, v67, v46, v66
	v_max3_f32 v64, v64, v65, v66
	v_mov_b32_e32 v65, v64
	s_nop 1
	v_permlane32_swap_b32_e32 v64, v65
	v_max_f32_e32 v65, v65, v65
	v_max_f32_e32 v64, v64, v64
	v_max_f32_e32 v64, v64, v65
	v_cmp_lt_f32_e32 vcc, s59, v64
	s_cbranch_vccnz .LBB0_861
	v_mov_b32_e32 v64, v151
	v_mov_b32_e32 v151, v152
	v_mov_b32_e32 v65, v153
	s_branch .LBB0_862

; __global__ void __launch_bounds__(512, 2) fwd_mega(Args a) {
	.amdhsa_kernel _Z8fwd_mega4Args
		.amdhsa_group_segment_fixed_size 0
		.amdhsa_private_segment_fixed_size 0
		.amdhsa_kernarg_size 496
		.amdhsa_user_sgpr_count 2
		.amdhsa_user_sgpr_dispatch_ptr 0
		.amdhsa_user_sgpr_queue_ptr 0
		.amdhsa_user_sgpr_kernarg_segment_ptr 1
		.amdhsa_user_sgpr_dispatch_id 0
		.amdhsa_user_sgpr_kernarg_preload_length 0
		.amdhsa_user_sgpr_kernarg_preload_offset 0
		.amdhsa_user_sgpr_private_segment_size 0
		.amdhsa_uses_dynamic_stack 0
		.amdhsa_enable_private_segment 0
		.amdhsa_system_sgpr_workgroup_id_x 1
		.amdhsa_system_sgpr_workgroup_id_y 0
		.amdhsa_system_sgpr_workgroup_id_z 0
		.amdhsa_system_sgpr_workgroup_info 0
		.amdhsa_system_vgpr_workitem_id 2
		.amdhsa_next_free_vgpr 252
		.amdhsa_next_free_sgpr 102
		.amdhsa_accum_offset 252
		.amdhsa_reserve_vcc 1
		.amdhsa_float_round_mode_32 0
		.amdhsa_float_round_mode_16_64 0
		.amdhsa_float_denorm_mode_32 3
		.amdhsa_float_denorm_mode_16_64 3
		.amdhsa_dx10_clamp 1
		.amdhsa_ieee_mode 1
		.amdhsa_fp16_overflow 0
		.amdhsa_tg_split 0
		.amdhsa_exception_fp_ieee_invalid_op 0
		.amdhsa_exception_fp_denorm_src 0
		.amdhsa_exception_fp_ieee_div_zero 0
		.amdhsa_exception_fp_ieee_overflow 0
		.amdhsa_exception_fp_ieee_underflow 0
		.amdhsa_exception_fp_ieee_inexact 0
		.amdhsa_exception_int_div_zero 0
	.end_amdhsa_kernel

; __global__ void __launch_bounds__(512, 2) fwd_mega(Args a) {
.Lfunc_end0:
	.size	_Z8fwd_mega4Args, .Lfunc_end0-_Z8fwd_mega4Args
	.set _Z8fwd_mega4Args.num_vgpr, 252
	.set _Z8fwd_mega4Args.num_agpr, 0
	.set _Z8fwd_mega4Args.numbered_sgpr, 98
	.set _Z8fwd_mega4Args.num_named_barrier, 0
	.set _Z8fwd_mega4Args.private_seg_size, 0
	.set _Z8fwd_mega4Args.uses_vcc, 1
	.set _Z8fwd_mega4Args.uses_flat_scratch, 0
	.set _Z8fwd_mega4Args.has_dyn_sized_stack, 0
	.set _Z8fwd_mega4Args.has_recursion, 0
	.set _Z8fwd_mega4Args.has_indirect_call, 0

; __global__ void __launch_bounds__(512, 2) fwd_mega(Args a) {
amdhsa.kernels:
  - .agpr_count:     0
    .args:
      - .offset:         0
        .size:           240
        .value_kind:     by_value
      - .offset:         240
        .size:           4
        .value_kind:     hidden_block_count_x
      - .offset:         244
        .size:           4
        .value_kind:     hidden_block_count_y
      - .offset:         248
        .size:           4
        .value_kind:     hidden_block_count_z
      - .offset:         252
        .size:           2
        .value_kind:     hidden_group_size_x
      - .offset:         254
        .size:           2
        .value_kind:     hidden_group_size_y
      - .offset:         256
        .size:           2
        .value_kind:     hidden_group_size_z
      - .offset:         258
        .size:           2
        .value_kind:     hidden_remainder_x
      - .offset:         260
        .size:           2
        .value_kind:     hidden_remainder_y
      - .offset:         262
        .size:           2
        .value_kind:     hidden_remainder_z
      - .offset:         280
        .size:           8
        .value_kind:     hidden_global_offset_x
      - .offset:         288
        .size:           8
        .value_kind:     hidden_global_offset_y
      - .offset:         296
        .size:           8
        .value_kind:     hidden_global_offset_z
      - .offset:         304
        .size:           2
        .value_kind:     hidden_grid_dims
      - .offset:         328
        .size:           8
        .value_kind:     hidden_multigrid_sync_arg
      - .offset:         360
        .size:           4
        .value_kind:     hidden_dynamic_lds_size
    .group_segment_fixed_size: 0
    .kernarg_segment_align: 8
    .kernarg_segment_size: 496
    .language:       OpenCL C
    .language_version:
      - 2
      - 0
    .max_flat_workgroup_size: 512
    .name:           _Z8fwd_mega4Args
    .private_segment_fixed_size: 0
    .sgpr_count:     108
    .sgpr_spill_count: 6
    .symbol:         _Z8fwd_mega4Args.kd
    .uniform_work_group_size: 1
    .uses_dynamic_stack: false
    .vgpr_count:     252
    .vgpr_spill_count: 0
    .wavefront_size: 64
